# merge mid-K gate hook, merge epilogue, out epilogue: batched loads with counted vmcnt instead of one round trip per tile; removed spurious vmcnt(0) in merge K-loop
# speedup vs baseline: 1.0415x; 1.0415x over previous
; DI bf16x4 pack4(float a, float b, float c, float d) { u32x2v u; u.x = pk2(a, b); u.y = pk2(c, d); return __builtin_bit_cast(bf16x4, u); }
;   DI void operator()(const f32x4 (&acc)[2][2][4][2], const pg8::Unit& u, int wr, int wc, int fr, int fq) const {
;     ...
;     for (int ai = 0; ai < 2; ++ai)
; #pragma unroll
;       for (int m = 0; m < 4; ++m) {
;         const int row = u.pm * 256 + 128 * ai + 64 * wr + 16 * m + fr;
; #pragma unroll
;         for (int bj = 0; bj < 2; ++bj)
; #pragma unroll
;           for (int n = 0; n < 2; ++n) {
;             const size_t idx = (size_t)row * 1024 + u.pn * 256 + 128 * bj + 32 * wc + 16 * n + 4 * fq;
;             const f32x4 a = acc[ai][bj][m][n];
;             if (MODE == 0) {
;               const unsigned g = *reinterpret_cast<const unsigned*>(reinterpret_cast<const unsigned char*>(p.ws + OFF_RB) + idx);
;               const float k = 1.f / 255.f;
;               st4(MERGED + idx, pack4((float)(g & 255u) * k * a[0], (float)((g >> 8) & 255u) * k * a[1], (float)((g >> 16) & 255u) * k * a[2], (float)(g >> 24) * k * a[3]));
.LBB0_2731:
	v_lshl_or_b32 v16, v148, 10, v138
	v_readlane_b32 s12, v250, 30
	v_readlane_b32 s13, v250, 31
	s_or_b32 s56, s29, s10
	s_mov_b32 s14, 0x3b808081
	v_or_b32_e32 v16, s56, v16
	v_lshlrev_b32_e32 v18, 1, v16
	s_add_u32 s56, s48, 0x0
	s_addc_u32 s57, s49, 0
	global_load_dword v204, v16, s[56:57]
	global_load_dword v205, v16, s[56:57] offset:16
	global_load_dword v206, v16, s[56:57] offset:128
	global_load_dword v207, v16, s[56:57] offset:144
	s_add_u32 s58, s48, 0x4000
	s_addc_u32 s59, s49, 0
	global_load_dword v208, v16, s[58:59]
	global_load_dword v209, v16, s[58:59] offset:16
	global_load_dword v210, v16, s[58:59] offset:128
	global_load_dword v211, v16, s[58:59] offset:144
	s_add_u32 s56, s48, 0x8000
	s_addc_u32 s57, s49, 0
	global_load_dword v212, v16, s[56:57]
	global_load_dword v213, v16, s[56:57] offset:16
	global_load_dword v214, v16, s[56:57] offset:128
	global_load_dword v215, v16, s[56:57] offset:144
	s_add_u32 s58, s48, 0xc000
	s_addc_u32 s59, s49, 0
	global_load_dword v216, v16, s[58:59]
	global_load_dword v217, v16, s[58:59] offset:16
	global_load_dword v218, v16, s[58:59] offset:128
	global_load_dword v219, v16, s[58:59] offset:144
	s_add_u32 s56, s48, 0x20000
	s_addc_u32 s57, s49, 0
	global_load_dword v220, v16, s[56:57]
	global_load_dword v221, v16, s[56:57] offset:16
	global_load_dword v222, v16, s[56:57] offset:128
	global_load_dword v223, v16, s[56:57] offset:144
	s_add_u32 s58, s48, 0x24000
	s_addc_u32 s59, s49, 0
	global_load_dword v224, v16, s[58:59]
	global_load_dword v225, v16, s[58:59] offset:16
	global_load_dword v226, v16, s[58:59] offset:128
	global_load_dword v227, v16, s[58:59] offset:144
	s_add_u32 s56, s48, 0x28000
	s_addc_u32 s57, s49, 0
	global_load_dword v228, v16, s[56:57]
	global_load_dword v229, v16, s[56:57] offset:16
	global_load_dword v230, v16, s[56:57] offset:128
	global_load_dword v231, v16, s[56:57] offset:144
	s_add_u32 s58, s48, 0x2c000
	s_addc_u32 s59, s49, 0
	global_load_dword v232, v16, s[58:59]
	global_load_dword v233, v16, s[58:59] offset:16
	global_load_dword v234, v16, s[58:59] offset:128
	global_load_dword v235, v16, s[58:59] offset:144
	s_add_u32 s60, s12, 0x0
	s_addc_u32 s61, s13, 0
	s_waitcnt vmcnt(31)
	v_cvt_f32_ubyte1_e32 v155, v204
	v_cvt_f32_ubyte0_e32 v154, v204
	v_cvt_f32_ubyte3_e32 v157, v204
	v_cvt_f32_ubyte2_e32 v156, v204
	v_pk_mul_f32 v[154:155], v[154:155], s[14:15] op_sel_hi:[1,0]
	v_pk_mul_f32 v[156:157], v[156:157], s[14:15] op_sel_hi:[1,0]
	v_pk_mul_f32 v[130:131], v[130:131], v[154:155]
	v_pk_mul_f32 v[132:133], v[132:133], v[156:157]
	v_cvt_pk_bf16_f32 v130, v130, v131
	v_cvt_pk_bf16_f32 v131, v132, v133
	global_store_dwordx2 v18, v[130:131], s[60:61]
	s_waitcnt vmcnt(31)
	v_cvt_f32_ubyte1_e32 v155, v205
	v_cvt_f32_ubyte0_e32 v154, v205
	v_cvt_f32_ubyte3_e32 v157, v205
	v_cvt_f32_ubyte2_e32 v156, v205
	v_pk_mul_f32 v[154:155], v[154:155], s[14:15] op_sel_hi:[1,0]
	v_pk_mul_f32 v[156:157], v[156:157], s[14:15] op_sel_hi:[1,0]
	v_pk_mul_f32 v[126:127], v[126:127], v[154:155]
	v_pk_mul_f32 v[128:129], v[128:129], v[156:157]
	v_cvt_pk_bf16_f32 v126, v126, v127
	v_cvt_pk_bf16_f32 v127, v128, v129
	global_store_dwordx2 v18, v[126:127], s[60:61] offset:32
	s_waitcnt vmcnt(31)
	v_cvt_f32_ubyte1_e32 v155, v206
	v_cvt_f32_ubyte0_e32 v154, v206
	v_cvt_f32_ubyte3_e32 v157, v206
	v_cvt_f32_ubyte2_e32 v156, v206
	v_pk_mul_f32 v[154:155], v[154:155], s[14:15] op_sel_hi:[1,0]
	v_pk_mul_f32 v[156:157], v[156:157], s[14:15] op_sel_hi:[1,0]
	v_pk_mul_f32 v[122:123], v[122:123], v[154:155]
	v_pk_mul_f32 v[124:125], v[124:125], v[156:157]
	v_cvt_pk_bf16_f32 v122, v122, v123
	v_cvt_pk_bf16_f32 v123, v124, v125
	global_store_dwordx2 v18, v[122:123], s[60:61] offset:256
	s_waitcnt vmcnt(31)
	v_cvt_f32_ubyte1_e32 v155, v207
	v_cvt_f32_ubyte0_e32 v154, v207
	v_cvt_f32_ubyte3_e32 v157, v207
	v_cvt_f32_ubyte2_e32 v156, v207
	v_pk_mul_f32 v[154:155], v[154:155], s[14:15] op_sel_hi:[1,0]
	v_pk_mul_f32 v[156:157], v[156:157], s[14:15] op_sel_hi:[1,0]
	v_pk_mul_f32 v[118:119], v[118:119], v[154:155]
	v_pk_mul_f32 v[120:121], v[120:121], v[156:157]
	v_cvt_pk_bf16_f32 v118, v118, v119
	v_cvt_pk_bf16_f32 v119, v120, v121
	global_store_dwordx2 v18, v[118:119], s[60:61] offset:288
	s_add_u32 s62, s12, 0x8000
	s_addc_u32 s63, s13, 0
	s_waitcnt vmcnt(31)
	v_cvt_f32_ubyte1_e32 v155, v208
	v_cvt_f32_ubyte0_e32 v154, v208
	v_cvt_f32_ubyte3_e32 v157, v208
	v_cvt_f32_ubyte2_e32 v156, v208
	v_pk_mul_f32 v[154:155], v[154:155], s[14:15] op_sel_hi:[1,0]
	v_pk_mul_f32 v[156:157], v[156:157], s[14:15] op_sel_hi:[1,0]
	v_pk_mul_f32 v[114:115], v[114:115], v[154:155]
	v_pk_mul_f32 v[116:117], v[116:117], v[156:157]
	v_cvt_pk_bf16_f32 v114, v114, v115
	v_cvt_pk_bf16_f32 v115, v116, v117
	global_store_dwordx2 v18, v[114:115], s[62:63]
	s_waitcnt vmcnt(31)
	v_cvt_f32_ubyte1_e32 v155, v209
	v_cvt_f32_ubyte0_e32 v154, v209
	v_cvt_f32_ubyte3_e32 v157, v209
	v_cvt_f32_ubyte2_e32 v156, v209
	v_pk_mul_f32 v[154:155], v[154:155], s[14:15] op_sel_hi:[1,0]
	v_pk_mul_f32 v[156:157], v[156:157], s[14:15] op_sel_hi:[1,0]
	v_pk_mul_f32 v[110:111], v[110:111], v[154:155]
	v_pk_mul_f32 v[112:113], v[112:113], v[156:157]
	v_cvt_pk_bf16_f32 v110, v110, v111
	v_cvt_pk_bf16_f32 v111, v112, v113
	global_store_dwordx2 v18, v[110:111], s[62:63] offset:32
	s_waitcnt vmcnt(31)
	v_cvt_f32_ubyte1_e32 v155, v210
	v_cvt_f32_ubyte0_e32 v154, v210
	v_cvt_f32_ubyte3_e32 v157, v210
	v_cvt_f32_ubyte2_e32 v156, v210
	v_pk_mul_f32 v[154:155], v[154:155], s[14:15] op_sel_hi:[1,0]
	v_pk_mul_f32 v[156:157], v[156:157], s[14:15] op_sel_hi:[1,0]
	v_pk_mul_f32 v[106:107], v[106:107], v[154:155]
	v_pk_mul_f32 v[108:109], v[108:109], v[156:157]
	v_cvt_pk_bf16_f32 v106, v106, v107
	v_cvt_pk_bf16_f32 v107, v108, v109
	global_store_dwordx2 v18, v[106:107], s[62:63] offset:256
	s_waitcnt vmcnt(31)
; DI bf16x4 pack4(float a, float b, float c, float d) { u32x2v u; u.x = pk2(a, b); u.y = pk2(c, d); return __builtin_bit_cast(bf16x4, u); }
;   DI void operator()(const f32x4 (&acc)[2][2][4][2], const pg8::Unit& u, int wr, int wc, int fr, int fq) const {
;     ...
;     for (int ai = 0; ai < 2; ++ai)
; #pragma unroll
;       for (int m = 0; m < 4; ++m) {
;         const int row = u.pm * 256 + 128 * ai + 64 * wr + 16 * m + fr;
; #pragma unroll
;         for (int bj = 0; bj < 2; ++bj)
; #pragma unroll
;           for (int n = 0; n < 2; ++n) {
;             const size_t idx = (size_t)row * 1024 + u.pn * 256 + 128 * bj + 32 * wc + 16 * n + 4 * fq;
;             const f32x4 a = acc[ai][bj][m][n];
;             if (MODE == 0) {
;               const unsigned g = *reinterpret_cast<const unsigned*>(reinterpret_cast<const unsigned char*>(p.ws + OFF_RB) + idx);
;               const float k = 1.f / 255.f;
;               st4(MERGED + idx, pack4((float)(g & 255u) * k * a[0], (float)((g >> 8) & 255u) * k * a[1], (float)((g >> 16) & 255u) * k * a[2], (float)(g >> 24) * k * a[3]));
	v_cvt_f32_ubyte1_e32 v155, v211
	v_cvt_f32_ubyte0_e32 v154, v211
	v_cvt_f32_ubyte3_e32 v157, v211
	v_cvt_f32_ubyte2_e32 v156, v211
	v_pk_mul_f32 v[154:155], v[154:155], s[14:15] op_sel_hi:[1,0]
	v_pk_mul_f32 v[156:157], v[156:157], s[14:15] op_sel_hi:[1,0]
	v_pk_mul_f32 v[102:103], v[102:103], v[154:155]
	v_pk_mul_f32 v[104:105], v[104:105], v[156:157]
	v_cvt_pk_bf16_f32 v102, v102, v103
	v_cvt_pk_bf16_f32 v103, v104, v105
	global_store_dwordx2 v18, v[102:103], s[62:63] offset:288
	s_add_u32 s60, s12, 0x10000
	s_addc_u32 s61, s13, 0
	s_waitcnt vmcnt(31)
	v_cvt_f32_ubyte1_e32 v155, v212
	v_cvt_f32_ubyte0_e32 v154, v212
	v_cvt_f32_ubyte3_e32 v157, v212
	v_cvt_f32_ubyte2_e32 v156, v212
	v_pk_mul_f32 v[154:155], v[154:155], s[14:15] op_sel_hi:[1,0]
	v_pk_mul_f32 v[156:157], v[156:157], s[14:15] op_sel_hi:[1,0]
	v_pk_mul_f32 v[98:99], v[98:99], v[154:155]
	v_pk_mul_f32 v[100:101], v[100:101], v[156:157]
	v_cvt_pk_bf16_f32 v98, v98, v99
	v_cvt_pk_bf16_f32 v99, v100, v101
	global_store_dwordx2 v18, v[98:99], s[60:61]
	s_waitcnt vmcnt(31)
	v_cvt_f32_ubyte1_e32 v155, v213
	v_cvt_f32_ubyte0_e32 v154, v213
	v_cvt_f32_ubyte3_e32 v157, v213
	v_cvt_f32_ubyte2_e32 v156, v213
	v_pk_mul_f32 v[154:155], v[154:155], s[14:15] op_sel_hi:[1,0]
	v_pk_mul_f32 v[156:157], v[156:157], s[14:15] op_sel_hi:[1,0]
	v_pk_mul_f32 v[94:95], v[94:95], v[154:155]
	v_pk_mul_f32 v[96:97], v[96:97], v[156:157]
	v_cvt_pk_bf16_f32 v94, v94, v95
	v_cvt_pk_bf16_f32 v95, v96, v97
	global_store_dwordx2 v18, v[94:95], s[60:61] offset:32
	s_waitcnt vmcnt(31)
	v_cvt_f32_ubyte1_e32 v155, v214
	v_cvt_f32_ubyte0_e32 v154, v214
	v_cvt_f32_ubyte3_e32 v157, v214
	v_cvt_f32_ubyte2_e32 v156, v214
	v_pk_mul_f32 v[154:155], v[154:155], s[14:15] op_sel_hi:[1,0]
	v_pk_mul_f32 v[156:157], v[156:157], s[14:15] op_sel_hi:[1,0]
	v_pk_mul_f32 v[90:91], v[90:91], v[154:155]
	v_pk_mul_f32 v[92:93], v[92:93], v[156:157]
	v_cvt_pk_bf16_f32 v90, v90, v91
	v_cvt_pk_bf16_f32 v91, v92, v93
	global_store_dwordx2 v18, v[90:91], s[60:61] offset:256
	s_waitcnt vmcnt(31)
	v_cvt_f32_ubyte1_e32 v155, v215
	v_cvt_f32_ubyte0_e32 v154, v215
	v_cvt_f32_ubyte3_e32 v157, v215
	v_cvt_f32_ubyte2_e32 v156, v215
	v_pk_mul_f32 v[154:155], v[154:155], s[14:15] op_sel_hi:[1,0]
	v_pk_mul_f32 v[156:157], v[156:157], s[14:15] op_sel_hi:[1,0]
	v_pk_mul_f32 v[86:87], v[86:87], v[154:155]
	v_pk_mul_f32 v[88:89], v[88:89], v[156:157]
	v_cvt_pk_bf16_f32 v86, v86, v87
	v_cvt_pk_bf16_f32 v87, v88, v89
	global_store_dwordx2 v18, v[86:87], s[60:61] offset:288
	s_add_u32 s62, s12, 0x18000
	s_addc_u32 s63, s13, 0
	s_waitcnt vmcnt(31)
	v_cvt_f32_ubyte1_e32 v155, v216
	v_cvt_f32_ubyte0_e32 v154, v216
	v_cvt_f32_ubyte3_e32 v157, v216
	v_cvt_f32_ubyte2_e32 v156, v216
	v_pk_mul_f32 v[154:155], v[154:155], s[14:15] op_sel_hi:[1,0]
	v_pk_mul_f32 v[156:157], v[156:157], s[14:15] op_sel_hi:[1,0]
	v_pk_mul_f32 v[82:83], v[82:83], v[154:155]
	v_pk_mul_f32 v[84:85], v[84:85], v[156:157]
	v_cvt_pk_bf16_f32 v82, v82, v83
	v_cvt_pk_bf16_f32 v83, v84, v85
	global_store_dwordx2 v18, v[82:83], s[62:63]
	s_waitcnt vmcnt(31)
	v_cvt_f32_ubyte1_e32 v155, v217
	v_cvt_f32_ubyte0_e32 v154, v217
	v_cvt_f32_ubyte3_e32 v157, v217
	v_cvt_f32_ubyte2_e32 v156, v217
	v_pk_mul_f32 v[154:155], v[154:155], s[14:15] op_sel_hi:[1,0]
	v_pk_mul_f32 v[156:157], v[156:157], s[14:15] op_sel_hi:[1,0]
	v_pk_mul_f32 v[78:79], v[78:79], v[154:155]
	v_pk_mul_f32 v[80:81], v[80:81], v[156:157]
	v_cvt_pk_bf16_f32 v78, v78, v79
	v_cvt_pk_bf16_f32 v79, v80, v81
	global_store_dwordx2 v18, v[78:79], s[62:63] offset:32
	s_waitcnt vmcnt(31)
	v_cvt_f32_ubyte1_e32 v155, v218
	v_cvt_f32_ubyte0_e32 v154, v218
	v_cvt_f32_ubyte3_e32 v157, v218
	v_cvt_f32_ubyte2_e32 v156, v218
	v_pk_mul_f32 v[154:155], v[154:155], s[14:15] op_sel_hi:[1,0]
	v_pk_mul_f32 v[156:157], v[156:157], s[14:15] op_sel_hi:[1,0]
	v_pk_mul_f32 v[74:75], v[74:75], v[154:155]
	v_pk_mul_f32 v[76:77], v[76:77], v[156:157]
	v_cvt_pk_bf16_f32 v74, v74, v75
	v_cvt_pk_bf16_f32 v75, v76, v77
	global_store_dwordx2 v18, v[74:75], s[62:63] offset:256
	s_waitcnt vmcnt(31)
	v_cvt_f32_ubyte1_e32 v155, v219
	v_cvt_f32_ubyte0_e32 v154, v219
	v_cvt_f32_ubyte3_e32 v157, v219
	v_cvt_f32_ubyte2_e32 v156, v219
	v_pk_mul_f32 v[154:155], v[154:155], s[14:15] op_sel_hi:[1,0]
	v_pk_mul_f32 v[156:157], v[156:157], s[14:15] op_sel_hi:[1,0]
	v_pk_mul_f32 v[70:71], v[70:71], v[154:155]
	v_pk_mul_f32 v[72:73], v[72:73], v[156:157]
	v_cvt_pk_bf16_f32 v70, v70, v71
	v_cvt_pk_bf16_f32 v71, v72, v73
	global_store_dwordx2 v18, v[70:71], s[62:63] offset:288
	s_add_u32 s60, s12, 0x40000
	s_addc_u32 s61, s13, 0
	s_waitcnt vmcnt(31)
	v_cvt_f32_ubyte1_e32 v155, v220
	v_cvt_f32_ubyte0_e32 v154, v220
	v_cvt_f32_ubyte3_e32 v157, v220
	v_cvt_f32_ubyte2_e32 v156, v220
	v_pk_mul_f32 v[154:155], v[154:155], s[14:15] op_sel_hi:[1,0]
	v_pk_mul_f32 v[156:157], v[156:157], s[14:15] op_sel_hi:[1,0]
	v_pk_mul_f32 v[66:67], v[66:67], v[154:155]
	v_pk_mul_f32 v[68:69], v[68:69], v[156:157]
	v_cvt_pk_bf16_f32 v66, v66, v67
	v_cvt_pk_bf16_f32 v67, v68, v69
	global_store_dwordx2 v18, v[66:67], s[60:61]
	s_waitcnt vmcnt(31)
	v_cvt_f32_ubyte1_e32 v155, v221
	v_cvt_f32_ubyte0_e32 v154, v221
	v_cvt_f32_ubyte3_e32 v157, v221
	v_cvt_f32_ubyte2_e32 v156, v221
	v_pk_mul_f32 v[154:155], v[154:155], s[14:15] op_sel_hi:[1,0]
	v_pk_mul_f32 v[156:157], v[156:157], s[14:15] op_sel_hi:[1,0]
	v_pk_mul_f32 v[62:63], v[62:63], v[154:155]
	v_pk_mul_f32 v[64:65], v[64:65], v[156:157]
	v_cvt_pk_bf16_f32 v62, v62, v63
	v_cvt_pk_bf16_f32 v63, v64, v65
	global_store_dwordx2 v18, v[62:63], s[60:61] offset:32
	s_waitcnt vmcnt(31)
; DI bf16x4 pack4(float a, float b, float c, float d) { u32x2v u; u.x = pk2(a, b); u.y = pk2(c, d); return __builtin_bit_cast(bf16x4, u); }
;   DI void operator()(const f32x4 (&acc)[2][2][4][2], const pg8::Unit& u, int wr, int wc, int fr, int fq) const {
;     ...
;     for (int ai = 0; ai < 2; ++ai)
; #pragma unroll
;       for (int m = 0; m < 4; ++m) {
;         const int row = u.pm * 256 + 128 * ai + 64 * wr + 16 * m + fr;
; #pragma unroll
;         for (int bj = 0; bj < 2; ++bj)
; #pragma unroll
;           for (int n = 0; n < 2; ++n) {
;             const size_t idx = (size_t)row * 1024 + u.pn * 256 + 128 * bj + 32 * wc + 16 * n + 4 * fq;
;             const f32x4 a = acc[ai][bj][m][n];
;             if (MODE == 0) {
;               const unsigned g = *reinterpret_cast<const unsigned*>(reinterpret_cast<const unsigned char*>(p.ws + OFF_RB) + idx);
;               const float k = 1.f / 255.f;
;               st4(MERGED + idx, pack4((float)(g & 255u) * k * a[0], (float)((g >> 8) & 255u) * k * a[1], (float)((g >> 16) & 255u) * k * a[2], (float)(g >> 24) * k * a[3]));
	v_cvt_f32_ubyte1_e32 v155, v222
	v_cvt_f32_ubyte0_e32 v154, v222
	v_cvt_f32_ubyte3_e32 v157, v222
	v_cvt_f32_ubyte2_e32 v156, v222
	v_pk_mul_f32 v[154:155], v[154:155], s[14:15] op_sel_hi:[1,0]
	v_pk_mul_f32 v[156:157], v[156:157], s[14:15] op_sel_hi:[1,0]
	v_pk_mul_f32 v[58:59], v[58:59], v[154:155]
	v_pk_mul_f32 v[60:61], v[60:61], v[156:157]
	v_cvt_pk_bf16_f32 v58, v58, v59
	v_cvt_pk_bf16_f32 v59, v60, v61
	global_store_dwordx2 v18, v[58:59], s[60:61] offset:256
	s_waitcnt vmcnt(31)
	v_cvt_f32_ubyte1_e32 v155, v223
	v_cvt_f32_ubyte0_e32 v154, v223
	v_cvt_f32_ubyte3_e32 v157, v223
	v_cvt_f32_ubyte2_e32 v156, v223
	v_pk_mul_f32 v[154:155], v[154:155], s[14:15] op_sel_hi:[1,0]
	v_pk_mul_f32 v[156:157], v[156:157], s[14:15] op_sel_hi:[1,0]
	v_pk_mul_f32 v[54:55], v[54:55], v[154:155]
	v_pk_mul_f32 v[56:57], v[56:57], v[156:157]
	v_cvt_pk_bf16_f32 v54, v54, v55
	v_cvt_pk_bf16_f32 v55, v56, v57
	global_store_dwordx2 v18, v[54:55], s[60:61] offset:288
	s_add_u32 s62, s12, 0x48000
	s_addc_u32 s63, s13, 0
	s_waitcnt vmcnt(31)
	v_cvt_f32_ubyte1_e32 v155, v224
	v_cvt_f32_ubyte0_e32 v154, v224
	v_cvt_f32_ubyte3_e32 v157, v224
	v_cvt_f32_ubyte2_e32 v156, v224
	v_pk_mul_f32 v[154:155], v[154:155], s[14:15] op_sel_hi:[1,0]
	v_pk_mul_f32 v[156:157], v[156:157], s[14:15] op_sel_hi:[1,0]
	v_pk_mul_f32 v[50:51], v[50:51], v[154:155]
	v_pk_mul_f32 v[52:53], v[52:53], v[156:157]
	v_cvt_pk_bf16_f32 v50, v50, v51
	v_cvt_pk_bf16_f32 v51, v52, v53
	global_store_dwordx2 v18, v[50:51], s[62:63]
	s_waitcnt vmcnt(31)
	v_cvt_f32_ubyte1_e32 v155, v225
	v_cvt_f32_ubyte0_e32 v154, v225
	v_cvt_f32_ubyte3_e32 v157, v225
	v_cvt_f32_ubyte2_e32 v156, v225
	v_pk_mul_f32 v[154:155], v[154:155], s[14:15] op_sel_hi:[1,0]
	v_pk_mul_f32 v[156:157], v[156:157], s[14:15] op_sel_hi:[1,0]
	v_pk_mul_f32 v[46:47], v[46:47], v[154:155]
	v_pk_mul_f32 v[48:49], v[48:49], v[156:157]
	v_cvt_pk_bf16_f32 v46, v46, v47
	v_cvt_pk_bf16_f32 v47, v48, v49
	global_store_dwordx2 v18, v[46:47], s[62:63] offset:32
	s_waitcnt vmcnt(31)
	v_cvt_f32_ubyte1_e32 v155, v226
	v_cvt_f32_ubyte0_e32 v154, v226
	v_cvt_f32_ubyte3_e32 v157, v226
	v_cvt_f32_ubyte2_e32 v156, v226
	v_pk_mul_f32 v[154:155], v[154:155], s[14:15] op_sel_hi:[1,0]
	v_pk_mul_f32 v[156:157], v[156:157], s[14:15] op_sel_hi:[1,0]
	v_pk_mul_f32 v[42:43], v[42:43], v[154:155]
	v_pk_mul_f32 v[44:45], v[44:45], v[156:157]
	v_cvt_pk_bf16_f32 v42, v42, v43
	v_cvt_pk_bf16_f32 v43, v44, v45
	global_store_dwordx2 v18, v[42:43], s[62:63] offset:256
	s_waitcnt vmcnt(31)
	v_cvt_f32_ubyte1_e32 v155, v227
	v_cvt_f32_ubyte0_e32 v154, v227
	v_cvt_f32_ubyte3_e32 v157, v227
	v_cvt_f32_ubyte2_e32 v156, v227
	v_pk_mul_f32 v[154:155], v[154:155], s[14:15] op_sel_hi:[1,0]
	v_pk_mul_f32 v[156:157], v[156:157], s[14:15] op_sel_hi:[1,0]
	v_pk_mul_f32 v[38:39], v[38:39], v[154:155]
	v_pk_mul_f32 v[40:41], v[40:41], v[156:157]
	v_cvt_pk_bf16_f32 v38, v38, v39
	v_cvt_pk_bf16_f32 v39, v40, v41
	global_store_dwordx2 v18, v[38:39], s[62:63] offset:288
	s_add_u32 s60, s12, 0x50000
	s_addc_u32 s61, s13, 0
	s_waitcnt vmcnt(31)
	v_cvt_f32_ubyte1_e32 v155, v228
	v_cvt_f32_ubyte0_e32 v154, v228
	v_cvt_f32_ubyte3_e32 v157, v228
	v_cvt_f32_ubyte2_e32 v156, v228
	v_pk_mul_f32 v[154:155], v[154:155], s[14:15] op_sel_hi:[1,0]
	v_pk_mul_f32 v[156:157], v[156:157], s[14:15] op_sel_hi:[1,0]
	v_pk_mul_f32 v[34:35], v[34:35], v[154:155]
	v_pk_mul_f32 v[36:37], v[36:37], v[156:157]
	v_cvt_pk_bf16_f32 v34, v34, v35
	v_cvt_pk_bf16_f32 v35, v36, v37
	global_store_dwordx2 v18, v[34:35], s[60:61]
	s_waitcnt vmcnt(31)
; DI bf16x4 pack4(float a, float b, float c, float d) { u32x2v u; u.x = pk2(a, b); u.y = pk2(c, d); return __builtin_bit_cast(bf16x4, u); }
; template <class Epi, class Sched>
; __device__ __forceinline__ void gemm_phase(PG8_LAS unsigned char* lds, const Gemm g, const Sched& S, const Epi& E) {
;     ...
;         if (!has_next) break;
;   DI void operator()(const f32x4 (&acc)[2][2][4][2], const pg8::Unit& u, int wr, int wc, int fr, int fq) const {
;     ...
;     for (int ai = 0; ai < 2; ++ai)
; #pragma unroll
;       for (int m = 0; m < 4; ++m) {
;         const int row = u.pm * 256 + 128 * ai + 64 * wr + 16 * m + fr;
; #pragma unroll
;         for (int bj = 0; bj < 2; ++bj)
; #pragma unroll
;           for (int n = 0; n < 2; ++n) {
;             const size_t idx = (size_t)row * 1024 + u.pn * 256 + 128 * bj + 32 * wc + 16 * n + 4 * fq;
;             const f32x4 a = acc[ai][bj][m][n];
;             if (MODE == 0) {
;               const unsigned g = *reinterpret_cast<const unsigned*>(reinterpret_cast<const unsigned char*>(p.ws + OFF_RB) + idx);
;               const float k = 1.f / 255.f;
;               st4(MERGED + idx, pack4((float)(g & 255u) * k * a[0], (float)((g >> 8) & 255u) * k * a[1], (float)((g >> 16) & 255u) * k * a[2], (float)(g >> 24) * k * a[3]));
	v_cvt_f32_ubyte1_e32 v155, v229
	v_cvt_f32_ubyte0_e32 v154, v229
	v_cvt_f32_ubyte3_e32 v157, v229
	v_cvt_f32_ubyte2_e32 v156, v229
	v_pk_mul_f32 v[154:155], v[154:155], s[14:15] op_sel_hi:[1,0]
	v_pk_mul_f32 v[156:157], v[156:157], s[14:15] op_sel_hi:[1,0]
	v_pk_mul_f32 v[30:31], v[30:31], v[154:155]
	v_pk_mul_f32 v[32:33], v[32:33], v[156:157]
	v_cvt_pk_bf16_f32 v30, v30, v31
	v_cvt_pk_bf16_f32 v31, v32, v33
	global_store_dwordx2 v18, v[30:31], s[60:61] offset:32
	s_waitcnt vmcnt(31)
	v_cvt_f32_ubyte1_e32 v155, v230
	v_cvt_f32_ubyte0_e32 v154, v230
	v_cvt_f32_ubyte3_e32 v157, v230
	v_cvt_f32_ubyte2_e32 v156, v230
	v_pk_mul_f32 v[154:155], v[154:155], s[14:15] op_sel_hi:[1,0]
	v_pk_mul_f32 v[156:157], v[156:157], s[14:15] op_sel_hi:[1,0]
	v_pk_mul_f32 v[26:27], v[26:27], v[154:155]
	v_pk_mul_f32 v[28:29], v[28:29], v[156:157]
	v_cvt_pk_bf16_f32 v26, v26, v27
	v_cvt_pk_bf16_f32 v27, v28, v29
	global_store_dwordx2 v18, v[26:27], s[60:61] offset:256
	s_waitcnt vmcnt(31)
	v_cvt_f32_ubyte1_e32 v155, v231
	v_cvt_f32_ubyte0_e32 v154, v231
	v_cvt_f32_ubyte3_e32 v157, v231
	v_cvt_f32_ubyte2_e32 v156, v231
	v_pk_mul_f32 v[154:155], v[154:155], s[14:15] op_sel_hi:[1,0]
	v_pk_mul_f32 v[156:157], v[156:157], s[14:15] op_sel_hi:[1,0]
	v_pk_mul_f32 v[22:23], v[22:23], v[154:155]
	v_pk_mul_f32 v[24:25], v[24:25], v[156:157]
	v_cvt_pk_bf16_f32 v22, v22, v23
	v_cvt_pk_bf16_f32 v23, v24, v25
	global_store_dwordx2 v18, v[22:23], s[60:61] offset:288
	s_add_u32 s62, s12, 0x58000
	s_addc_u32 s63, s13, 0
	s_waitcnt vmcnt(31)
	v_cvt_f32_ubyte1_e32 v155, v232
	v_cvt_f32_ubyte0_e32 v154, v232
	v_cvt_f32_ubyte3_e32 v157, v232
	v_cvt_f32_ubyte2_e32 v156, v232
	v_pk_mul_f32 v[154:155], v[154:155], s[14:15] op_sel_hi:[1,0]
	v_pk_mul_f32 v[156:157], v[156:157], s[14:15] op_sel_hi:[1,0]
	v_pk_mul_f32 v[12:13], v[12:13], v[154:155]
	v_pk_mul_f32 v[14:15], v[14:15], v[156:157]
	v_cvt_pk_bf16_f32 v12, v12, v13
	v_cvt_pk_bf16_f32 v13, v14, v15
	global_store_dwordx2 v18, v[12:13], s[62:63]
	s_waitcnt vmcnt(31)
	v_cvt_f32_ubyte1_e32 v155, v233
	v_cvt_f32_ubyte0_e32 v154, v233
	v_cvt_f32_ubyte3_e32 v157, v233
	v_cvt_f32_ubyte2_e32 v156, v233
	v_pk_mul_f32 v[154:155], v[154:155], s[14:15] op_sel_hi:[1,0]
	v_pk_mul_f32 v[156:157], v[156:157], s[14:15] op_sel_hi:[1,0]
	v_pk_mul_f32 v[8:9], v[8:9], v[154:155]
	v_pk_mul_f32 v[10:11], v[10:11], v[156:157]
	v_cvt_pk_bf16_f32 v8, v8, v9
	v_cvt_pk_bf16_f32 v9, v10, v11
	global_store_dwordx2 v18, v[8:9], s[62:63] offset:32
	s_waitcnt vmcnt(31)
	v_cvt_f32_ubyte1_e32 v155, v234
	v_cvt_f32_ubyte0_e32 v154, v234
	v_cvt_f32_ubyte3_e32 v157, v234
	v_cvt_f32_ubyte2_e32 v156, v234
	v_pk_mul_f32 v[154:155], v[154:155], s[14:15] op_sel_hi:[1,0]
	v_pk_mul_f32 v[156:157], v[156:157], s[14:15] op_sel_hi:[1,0]
	v_pk_mul_f32 v[4:5], v[4:5], v[154:155]
	v_pk_mul_f32 v[6:7], v[6:7], v[156:157]
	v_cvt_pk_bf16_f32 v4, v4, v5
	v_cvt_pk_bf16_f32 v5, v6, v7
	global_store_dwordx2 v18, v[4:5], s[62:63] offset:256
	s_waitcnt vmcnt(31)
	v_cvt_f32_ubyte1_e32 v155, v235
	v_cvt_f32_ubyte0_e32 v154, v235
	v_cvt_f32_ubyte3_e32 v157, v235
	v_cvt_f32_ubyte2_e32 v156, v235
	v_pk_mul_f32 v[154:155], v[154:155], s[14:15] op_sel_hi:[1,0]
	v_pk_mul_f32 v[156:157], v[156:157], s[14:15] op_sel_hi:[1,0]
	v_pk_mul_f32 v[0:1], v[0:1], v[154:155]
	v_pk_mul_f32 v[2:3], v[2:3], v[156:157]
	v_cvt_pk_bf16_f32 v0, v0, v1
	v_cvt_pk_bf16_f32 v1, v2, v3
	global_store_dwordx2 v18, v[0:1], s[62:63] offset:288
	s_mov_b32 s11, s2
	s_mov_b32 s10, s4
	s_mov_b64 s[12:13], s[6:7]
	s_mov_b64 s[14:15], s[8:9]
	s_and_b64 vcc, exec, s[0:1]
	s_cbranch_vccnz .LBB0_2738

; #define PG8_STAGE(bufoff, gbase, voff) do { _Pragma("unroll") for (int _i = 0; _i < 2; ++_i) \
;         __builtin_amdgcn_global_load_lds((const unsigned*)((const char*)(gbase) + (voff)[_i]), (PG8_LAS unsigned*)(lds + (bufoff) + ldsw + _i * 8192), 16, 0, 0); } while (0)
; #define PG8_LDA(dst, b, h) do { _Pragma("unroll") for (int m = 0; m < 4; ++m) _Pragma("unroll") for (int k = 0; k < 2; ++k) dst[m][k] = *(const PG8_LAS bf16x8*)(lds + PG8_SA(b, h) + aoff + m * 2048 + k * 1024); } while (0)
; #define PG8_LDB(dst, b, h) do { _Pragma("unroll") for (int n = 0; n < 2; ++n) _Pragma("unroll") for (int k = 0; k < 2; ++k) dst[n][k] = *(const PG8_LAS bf16x8*)(lds + PG8_SB(b, h) + boff + n * 2048 + k * 1024); } while (0)
; #define PG8_MMA(ai, bj, At, Bt) do { __builtin_amdgcn_s_setprio(1); _Pragma("unroll") for (int m = 0; m < 4; ++m) _Pragma("unroll") for (int n = 0; n < 2; ++n) _Pragma("unroll") for (int k = 0; k < 2; ++k) \
;         acc[ai][bj][m][n] = __builtin_amdgcn_mfma_f32_16x16x32_bf16(Bt[n][k], At[m][k], acc[ai][bj][m][n], 0, 0, 0); __builtin_amdgcn_s_setprio(0); } while (0)
; #define PG8_WAIT_V(n) asm volatile("s_waitcnt vmcnt(" #n ")" ::: "memory")
; #define PG8_WAIT_L(n) asm volatile("s_waitcnt lgkmcnt(" #n ")" ::: "memory")
; #define PG8_BAR __builtin_amdgcn_s_barrier()
; #define PG8_SCHED __builtin_amdgcn_sched_barrier(0)
; template <class Epi, class Sched>
; __device__ __forceinline__ void gemm_phase(PG8_LAS unsigned char* lds, const Gemm g, const Sched& S, const Epi& E) {
;     ...
;             PG8_LDB(B0, 0, 0); PG8_SCHED; PG8_LDA(At, 0, 0); PG8_STAGE(PG8_SA(1, 1), a1 + hstep, voffA);
;             PG8_WAIT_L(8); PG8_BAR; PG8_WAIT_L(0); PG8_MMA(0, 0, At, B0); PG8_BAR; PG8_SCHED;
;             PG8_LDB(B1, 0, 1); PG8_STAGE(PG8_SB(0, 0), b2, voffB);
;             PG8_BAR; PG8_WAIT_L(0); PG8_MMA(0, 1, At, B1); PG8_BAR;
;             PG8_LDA(At, 0, 1); PG8_STAGE(PG8_SA(0, 0), a2, voffA);
;             PG8_BAR; PG8_WAIT_L(0); PG8_MMA(1, 0, At, B0); PG8_BAR; PG8_SCHED;
;             PG8_STAGE(PG8_SB(0, 1), b2 + hstep, voffB);
;             PG8_WAIT_V(6); PG8_BAR; PG8_MMA(1, 1, At, B1); PG8_BAR;
.LBB0_2735:
	s_add_u32 s16, s12, s14
	s_addc_u32 s17, s13, s15
	s_add_u32 s16, s16, 0x100
	s_addc_u32 s17, s17, 0
	s_add_u32 s33, s39, s14
	s_addc_u32 s42, s40, s15
	s_cmpk_eq_i32 s14, 0x700
	s_cselect_b32 s19, s5, s17
	s_cselect_b32 s18, s36, s16
	s_cselect_b32 s17, s37, s42
	s_cselect_b32 s16, s38, s33
	s_add_i32 s33, 0, 0x10000
	v_add_u32_e32 v16, s33, v139
	ds_read_b128 v[178:181], v16
	ds_read_b128 v[188:191], v16 offset:1024
	ds_read_b128 v[192:195], v16 offset:2048
	ds_read_b128 v[196:199], v16 offset:3072
	v_lshl_add_u64 v[18:19], v[162:163], 0, s[14:15]
	s_add_i32 m0, s25, 0xc000
	ds_read_b128 v[200:203], v171
	ds_read_b128 v[204:207], v171 offset:1024
	ds_read_b128 v[208:211], v171 offset:2048
	ds_read_b128 v[212:215], v171 offset:3072
	ds_read_b128 v[216:219], v171 offset:4096
	ds_read_b128 v[220:223], v171 offset:5120
	ds_read_b128 v[224:227], v171 offset:6144
	ds_read_b128 v[228:231], v171 offset:7168
	global_load_lds_dwordx4 v[18:19], off
	v_lshl_add_u64 v[18:19], v[164:165], 0, s[14:15]
	s_add_i32 m0, s25, 0xe000
	s_nop 0
	global_load_lds_dwordx4 v[18:19], off
	s_waitcnt lgkmcnt(8)
	s_barrier
	s_waitcnt lgkmcnt(0)
	s_setprio 1
	s_waitcnt lgkmcnt(0)
	v_mfma_f32_16x16x32_bf16 v[130:133], v[178:181], v[200:203], v[130:133]
	v_mfma_f32_16x16x32_bf16 v[126:129], v[192:195], v[200:203], v[126:129]
	v_mfma_f32_16x16x32_bf16 v[114:117], v[178:181], v[208:211], v[114:117]
	v_mfma_f32_16x16x32_bf16 v[110:113], v[192:195], v[208:211], v[110:113]
	v_mfma_f32_16x16x32_bf16 v[98:101], v[178:181], v[216:219], v[98:101]
	v_mfma_f32_16x16x32_bf16 v[94:97], v[192:195], v[216:219], v[94:97]
	v_mfma_f32_16x16x32_bf16 v[82:85], v[178:181], v[224:227], v[82:85]
	v_mfma_f32_16x16x32_bf16 v[78:81], v[192:195], v[224:227], v[78:81]
	v_mfma_f32_16x16x32_bf16 v[130:133], v[188:191], v[204:207], v[130:133]
	v_mfma_f32_16x16x32_bf16 v[126:129], v[196:199], v[204:207], v[126:129]
	v_mfma_f32_16x16x32_bf16 v[114:117], v[188:191], v[212:215], v[114:117]
	v_mfma_f32_16x16x32_bf16 v[110:113], v[196:199], v[212:215], v[110:113]
	v_mfma_f32_16x16x32_bf16 v[98:101], v[188:191], v[220:223], v[98:101]
	v_mfma_f32_16x16x32_bf16 v[94:97], v[196:199], v[220:223], v[94:97]
	v_mfma_f32_16x16x32_bf16 v[82:85], v[188:191], v[228:231], v[82:85]
	v_mfma_f32_16x16x32_bf16 v[78:81], v[196:199], v[228:231], v[78:81]
	s_setprio 0
	s_barrier
	s_add_i32 s44, 0, 0x14000
	s_add_i32 s33, s33, s23
	v_add_u32_e32 v16, s44, v139
	v_lshl_add_u64 v[18:19], s[16:17], 0, v[136:137]
	s_mov_b32 m0, s33
	ds_read_b128 v[232:235], v16
	ds_read_b128 v[236:239], v16 offset:1024
	ds_read_b128 v[240:243], v16 offset:2048
	ds_read_b128 v[244:247], v16 offset:3072
	global_load_lds_dwordx4 v[18:19], off
	v_lshl_add_u64 v[186:187], s[16:17], 0, v[134:135]
	s_add_i32 m0, s33, 0x2000
	s_nop 0
	global_load_lds_dwordx4 v[186:187], off
	s_barrier
	s_waitcnt lgkmcnt(0)
	s_setprio 1
	s_waitcnt lgkmcnt(0)
	v_mfma_f32_16x16x32_bf16 v[122:125], v[232:235], v[200:203], v[122:125]
	v_mfma_f32_16x16x32_bf16 v[118:121], v[240:243], v[200:203], v[118:121]
	v_mfma_f32_16x16x32_bf16 v[106:109], v[232:235], v[208:211], v[106:109]
	v_mfma_f32_16x16x32_bf16 v[102:105], v[240:243], v[208:211], v[102:105]
	v_mfma_f32_16x16x32_bf16 v[90:93], v[232:235], v[216:219], v[90:93]
	v_mfma_f32_16x16x32_bf16 v[86:89], v[240:243], v[216:219], v[86:89]
	v_mfma_f32_16x16x32_bf16 v[74:77], v[232:235], v[224:227], v[74:77]
	v_mfma_f32_16x16x32_bf16 v[70:73], v[240:243], v[224:227], v[70:73]
	v_mfma_f32_16x16x32_bf16 v[122:125], v[236:239], v[204:207], v[122:125]
	v_mfma_f32_16x16x32_bf16 v[118:121], v[244:247], v[204:207], v[118:121]
	v_mfma_f32_16x16x32_bf16 v[106:109], v[236:239], v[212:215], v[106:109]
	v_mfma_f32_16x16x32_bf16 v[102:105], v[244:247], v[212:215], v[102:105]
	v_mfma_f32_16x16x32_bf16 v[90:93], v[236:239], v[220:223], v[90:93]
	v_mfma_f32_16x16x32_bf16 v[86:89], v[244:247], v[220:223], v[86:89]
	v_mfma_f32_16x16x32_bf16 v[74:77], v[236:239], v[228:231], v[74:77]
	v_mfma_f32_16x16x32_bf16 v[70:73], v[244:247], v[228:231], v[70:73]
	s_setprio 0
	s_mov_b32 m0, s25
	v_lshl_add_u64 v[154:155], s[18:19], 0, v[136:137]
	s_barrier
	ds_read_b128 v[200:203], v171 offset:16384
	ds_read_b128 v[204:207], v171 offset:17408
	ds_read_b128 v[208:211], v171 offset:18432
	ds_read_b128 v[212:215], v171 offset:19456
	ds_read_b128 v[216:219], v171 offset:20480
	ds_read_b128 v[220:223], v171 offset:21504
	ds_read_b128 v[224:227], v171 offset:22528
	ds_read_b128 v[228:231], v171 offset:23552
	global_load_lds_dwordx4 v[154:155], off
	v_lshl_add_u64 v[156:157], s[18:19], 0, v[134:135]
	s_mov_b32 m0, s26
	s_nop 0
	global_load_lds_dwordx4 v[156:157], off
	s_barrier
	s_waitcnt lgkmcnt(0)
	s_setprio 1
	s_waitcnt lgkmcnt(0)
	v_mfma_f32_16x16x32_bf16 v[66:69], v[178:181], v[200:203], v[66:69]
	v_mfma_f32_16x16x32_bf16 v[62:65], v[192:195], v[200:203], v[62:65]
	v_mfma_f32_16x16x32_bf16 v[50:53], v[178:181], v[208:211], v[50:53]
	v_mfma_f32_16x16x32_bf16 v[46:49], v[192:195], v[208:211], v[46:49]
	v_mfma_f32_16x16x32_bf16 v[34:37], v[178:181], v[216:219], v[34:37]
	v_mfma_f32_16x16x32_bf16 v[30:33], v[192:195], v[216:219], v[30:33]
	v_mfma_f32_16x16x32_bf16 v[12:15], v[178:181], v[224:227], v[12:15]
	v_mfma_f32_16x16x32_bf16 v[8:11], v[192:195], v[224:227], v[8:11]
	v_mfma_f32_16x16x32_bf16 v[66:69], v[188:191], v[204:207], v[66:69]
	v_mfma_f32_16x16x32_bf16 v[62:65], v[196:199], v[204:207], v[62:65]
	v_mfma_f32_16x16x32_bf16 v[50:53], v[188:191], v[212:215], v[50:53]
	v_mfma_f32_16x16x32_bf16 v[46:49], v[196:199], v[212:215], v[46:49]
	v_mfma_f32_16x16x32_bf16 v[34:37], v[188:191], v[220:223], v[34:37]
	v_mfma_f32_16x16x32_bf16 v[30:33], v[196:199], v[220:223], v[30:33]
	v_mfma_f32_16x16x32_bf16 v[12:15], v[188:191], v[228:231], v[12:15]
	v_mfma_f32_16x16x32_bf16 v[8:11], v[196:199], v[228:231], v[8:11]
	s_setprio 0
	s_barrier
; #define PG8_STAGE(bufoff, gbase, voff) do { _Pragma("unroll") for (int _i = 0; _i < 2; ++_i) \
;         __builtin_amdgcn_global_load_lds((const unsigned*)((const char*)(gbase) + (voff)[_i]), (PG8_LAS unsigned*)(lds + (bufoff) + ldsw + _i * 8192), 16, 0, 0); } while (0)
; #define PG8_LDA(dst, b, h) do { _Pragma("unroll") for (int m = 0; m < 4; ++m) _Pragma("unroll") for (int k = 0; k < 2; ++k) dst[m][k] = *(const PG8_LAS bf16x8*)(lds + PG8_SA(b, h) + aoff + m * 2048 + k * 1024); } while (0)
; #define PG8_LDB(dst, b, h) do { _Pragma("unroll") for (int n = 0; n < 2; ++n) _Pragma("unroll") for (int k = 0; k < 2; ++k) dst[n][k] = *(const PG8_LAS bf16x8*)(lds + PG8_SB(b, h) + boff + n * 2048 + k * 1024); } while (0)
; #define PG8_MMA(ai, bj, At, Bt) do { __builtin_amdgcn_s_setprio(1); _Pragma("unroll") for (int m = 0; m < 4; ++m) _Pragma("unroll") for (int n = 0; n < 2; ++n) _Pragma("unroll") for (int k = 0; k < 2; ++k) \
;         acc[ai][bj][m][n] = __builtin_amdgcn_mfma_f32_16x16x32_bf16(Bt[n][k], At[m][k], acc[ai][bj][m][n], 0, 0, 0); __builtin_amdgcn_s_setprio(0); } while (0)
; #define PG8_WAIT_V(n) asm volatile("s_waitcnt vmcnt(" #n ")" ::: "memory")
; #define PG8_WAIT_L(n) asm volatile("s_waitcnt lgkmcnt(" #n ")" ::: "memory")
; #define PG8_BAR __builtin_amdgcn_s_barrier()
; #define PG8_SCHED __builtin_amdgcn_sched_barrier(0)
; template <class Epi, class Sched>
; __device__ __forceinline__ void gemm_phase(PG8_LAS unsigned char* lds, const Gemm g, const Sched& S, const Epi& E) {
;     ...
;             PG8_WAIT_V(6); PG8_BAR; PG8_MMA(1, 1, At, B1); PG8_BAR;
;             PG8_LDB(B0, 1, 0); PG8_SCHED; PG8_LDA(At, 1, 0); PG8_STAGE(PG8_SA(0, 1), a2 + hstep, voffA);
;             PG8_WAIT_L(8); PG8_BAR; PG8_WAIT_L(0); PG8_MMA(0, 0, At, B0); PG8_BAR; PG8_SCHED;
;             PG8_LDB(B1, 1, 1); PG8_STAGE(PG8_SB(1, 0), b3, voffB);
;             PG8_BAR; PG8_WAIT_L(0); PG8_MMA(0, 1, At, B1); PG8_BAR;
;             PG8_LDA(At, 1, 1); PG8_STAGE(PG8_SA(1, 0), a3, voffA);
;             PG8_BAR; PG8_WAIT_L(0); PG8_MMA(1, 0, At, B0); PG8_BAR; PG8_SCHED;
	s_add_u32 s42, s16, 0x40000
	s_addc_u32 s43, s17, 0
	s_add_i32 s33, s44, s23
	v_lshl_add_u64 v[178:179], s[42:43], 0, v[136:137]
	s_mov_b32 m0, s33
	s_nop 0
	global_load_lds_dwordx4 v[178:179], off
	v_lshl_add_u64 v[178:179], s[42:43], 0, v[134:135]
	s_add_i32 m0, s33, 0x2000
	s_nop 0
	global_load_lds_dwordx4 v[178:179], off
	s_waitcnt vmcnt(6)
	s_barrier
	s_setprio 1
	v_mfma_f32_16x16x32_bf16 v[58:61], v[232:235], v[200:203], v[58:61]
	v_mfma_f32_16x16x32_bf16 v[54:57], v[240:243], v[200:203], v[54:57]
	v_mfma_f32_16x16x32_bf16 v[42:45], v[232:235], v[208:211], v[42:45]
	v_mfma_f32_16x16x32_bf16 v[38:41], v[240:243], v[208:211], v[38:41]
	v_mfma_f32_16x16x32_bf16 v[26:29], v[232:235], v[216:219], v[26:29]
	v_mfma_f32_16x16x32_bf16 v[22:25], v[240:243], v[216:219], v[22:25]
	v_mfma_f32_16x16x32_bf16 v[4:7], v[232:235], v[224:227], v[4:7]
	v_mfma_f32_16x16x32_bf16 v[0:3], v[240:243], v[224:227], v[0:3]
	v_mfma_f32_16x16x32_bf16 v[58:61], v[236:239], v[204:207], v[58:61]
	v_mfma_f32_16x16x32_bf16 v[54:57], v[244:247], v[204:207], v[54:57]
	v_mfma_f32_16x16x32_bf16 v[42:45], v[236:239], v[212:215], v[42:45]
	v_mfma_f32_16x16x32_bf16 v[38:41], v[244:247], v[212:215], v[38:41]
	v_mfma_f32_16x16x32_bf16 v[26:29], v[236:239], v[220:223], v[26:29]
	v_mfma_f32_16x16x32_bf16 v[22:25], v[244:247], v[220:223], v[22:25]
	v_mfma_f32_16x16x32_bf16 v[4:7], v[236:239], v[228:231], v[4:7]
	v_mfma_f32_16x16x32_bf16 v[0:3], v[244:247], v[228:231], v[0:3]
	s_setprio 0
	s_add_i32 s33, 0, 0x18000
	v_add_u32_e32 v16, s33, v139
	s_barrier
	ds_read_b128 v[178:181], v16
	ds_read_b128 v[188:191], v16 offset:1024
	ds_read_b128 v[192:195], v16 offset:2048
	ds_read_b128 v[196:199], v16 offset:3072
	s_add_u32 s18, s18, 0x40000
	s_addc_u32 s19, s19, 0
	s_mov_b32 m0, s27
	v_lshl_add_u64 v[232:233], s[18:19], 0, v[136:137]
	ds_read_b128 v[200:203], v171 offset:32768
	ds_read_b128 v[204:207], v171 offset:33792
	ds_read_b128 v[208:211], v171 offset:34816
	ds_read_b128 v[212:215], v171 offset:35840
	ds_read_b128 v[216:219], v171 offset:36864
	ds_read_b128 v[220:223], v171 offset:37888
	ds_read_b128 v[224:227], v171 offset:38912
	ds_read_b128 v[228:231], v171 offset:39936
	global_load_lds_dwordx4 v[232:233], off
	v_lshl_add_u64 v[232:233], s[18:19], 0, v[134:135]
	s_mov_b32 m0, s28
	s_nop 0
	global_load_lds_dwordx4 v[232:233], off
	s_waitcnt lgkmcnt(8)
	s_barrier
	s_waitcnt lgkmcnt(0)
	s_setprio 1
	s_waitcnt lgkmcnt(0)
	v_mfma_f32_16x16x32_bf16 v[130:133], v[178:181], v[200:203], v[130:133]
	v_mfma_f32_16x16x32_bf16 v[126:129], v[192:195], v[200:203], v[126:129]
	v_mfma_f32_16x16x32_bf16 v[114:117], v[178:181], v[208:211], v[114:117]
	v_mfma_f32_16x16x32_bf16 v[110:113], v[192:195], v[208:211], v[110:113]
	v_mfma_f32_16x16x32_bf16 v[98:101], v[178:181], v[216:219], v[98:101]
	v_mfma_f32_16x16x32_bf16 v[94:97], v[192:195], v[216:219], v[94:97]
	v_mfma_f32_16x16x32_bf16 v[82:85], v[178:181], v[224:227], v[82:85]
	v_mfma_f32_16x16x32_bf16 v[78:81], v[192:195], v[224:227], v[78:81]
	v_mfma_f32_16x16x32_bf16 v[130:133], v[188:191], v[204:207], v[130:133]
	v_mfma_f32_16x16x32_bf16 v[126:129], v[196:199], v[204:207], v[126:129]
	v_mfma_f32_16x16x32_bf16 v[114:117], v[188:191], v[212:215], v[114:117]
	v_mfma_f32_16x16x32_bf16 v[110:113], v[196:199], v[212:215], v[110:113]
	v_mfma_f32_16x16x32_bf16 v[98:101], v[188:191], v[220:223], v[98:101]
	v_mfma_f32_16x16x32_bf16 v[94:97], v[196:199], v[220:223], v[94:97]
	v_mfma_f32_16x16x32_bf16 v[82:85], v[188:191], v[228:231], v[82:85]
	v_mfma_f32_16x16x32_bf16 v[78:81], v[196:199], v[228:231], v[78:81]
	s_setprio 0
	s_barrier
	s_add_i32 s18, 0, 0x1c000
	s_mov_b64 s[42:43], 0x80
	s_add_i32 s19, s33, s23
	v_add_u32_e32 v16, s18, v139
	v_lshl_add_u64 v[18:19], v[18:19], 0, s[42:43]
	s_mov_b32 m0, s19
	ds_read_b128 v[232:235], v16
	ds_read_b128 v[236:239], v16 offset:1024
	ds_read_b128 v[240:243], v16 offset:2048
	ds_read_b128 v[244:247], v16 offset:3072
	global_load_lds_dwordx4 v[18:19], off
	v_lshl_add_u64 v[18:19], v[186:187], 0, s[42:43]
	s_add_i32 m0, s19, 0x2000
	s_nop 0
	global_load_lds_dwordx4 v[18:19], off
	s_barrier
	s_waitcnt lgkmcnt(0)
	s_setprio 1
	s_waitcnt lgkmcnt(0)
	v_mfma_f32_16x16x32_bf16 v[122:125], v[232:235], v[200:203], v[122:125]
	v_mfma_f32_16x16x32_bf16 v[118:121], v[240:243], v[200:203], v[118:121]
	v_mfma_f32_16x16x32_bf16 v[106:109], v[232:235], v[208:211], v[106:109]
	v_mfma_f32_16x16x32_bf16 v[102:105], v[240:243], v[208:211], v[102:105]
	v_mfma_f32_16x16x32_bf16 v[90:93], v[232:235], v[216:219], v[90:93]
	v_mfma_f32_16x16x32_bf16 v[86:89], v[240:243], v[216:219], v[86:89]
	v_mfma_f32_16x16x32_bf16 v[74:77], v[232:235], v[224:227], v[74:77]
	v_mfma_f32_16x16x32_bf16 v[70:73], v[240:243], v[224:227], v[70:73]
	v_mfma_f32_16x16x32_bf16 v[122:125], v[236:239], v[204:207], v[122:125]
	v_mfma_f32_16x16x32_bf16 v[118:121], v[244:247], v[204:207], v[118:121]
	v_mfma_f32_16x16x32_bf16 v[106:109], v[236:239], v[212:215], v[106:109]
	v_mfma_f32_16x16x32_bf16 v[102:105], v[244:247], v[212:215], v[102:105]
	v_mfma_f32_16x16x32_bf16 v[90:93], v[236:239], v[220:223], v[90:93]
	v_mfma_f32_16x16x32_bf16 v[86:89], v[244:247], v[220:223], v[86:89]
	v_mfma_f32_16x16x32_bf16 v[74:77], v[236:239], v[228:231], v[74:77]
	v_mfma_f32_16x16x32_bf16 v[70:73], v[244:247], v[228:231], v[70:73]
	s_setprio 0
	s_mov_b32 m0, s30
	v_lshl_add_u64 v[18:19], v[154:155], 0, s[42:43]
	s_barrier
; #define PG8_STAGE(bufoff, gbase, voff) do { _Pragma("unroll") for (int _i = 0; _i < 2; ++_i) \
;         __builtin_amdgcn_global_load_lds((const unsigned*)((const char*)(gbase) + (voff)[_i]), (PG8_LAS unsigned*)(lds + (bufoff) + ldsw + _i * 8192), 16, 0, 0); } while (0)
; #define PG8_MMA(ai, bj, At, Bt) do { __builtin_amdgcn_s_setprio(1); _Pragma("unroll") for (int m = 0; m < 4; ++m) _Pragma("unroll") for (int n = 0; n < 2; ++n) _Pragma("unroll") for (int k = 0; k < 2; ++k) \
;         acc[ai][bj][m][n] = __builtin_amdgcn_mfma_f32_16x16x32_bf16(Bt[n][k], At[m][k], acc[ai][bj][m][n], 0, 0, 0); __builtin_amdgcn_s_setprio(0); } while (0)
; #define PG8_WAIT_V(n) asm volatile("s_waitcnt vmcnt(" #n ")" ::: "memory")
; #define PG8_WAIT_L(n) asm volatile("s_waitcnt lgkmcnt(" #n ")" ::: "memory")
; #define PG8_BAR __builtin_amdgcn_s_barrier()
; #define PG8_SCHED __builtin_amdgcn_sched_barrier(0)
; template <class Epi, class Sched>
; __device__ __forceinline__ void gemm_phase(PG8_LAS unsigned char* lds, const Gemm g, const Sched& S, const Epi& E) {
;     ...
;             PG8_BAR; PG8_WAIT_L(0); PG8_MMA(1, 0, At, B0); PG8_BAR; PG8_SCHED;
;             PG8_STAGE(PG8_SB(1, 1), b3 + hstep, voffB);
;             PG8_WAIT_V(6); PG8_BAR; PG8_MMA(1, 1, At, B1); PG8_BAR;
;   DI void mid(f32x4 (&acc)[2][2][4][2], const pg8::Unit& u, int wr, int wc, int fr, int fq) const {
; #pragma unroll
;     for (int ai = 0; ai < 2; ++ai)
; #pragma unroll
;       for (int m = 0; m < 4; ++m) {
;         int row = u.pm * 256 + 128 * ai + 64 * wr + 16 * m + fr;
;         asm volatile("" : "+v"(row));
; #pragma unroll
;         for (int bj = 0; bj < 2; ++bj)
; #pragma unroll
;           for (int n = 0; n < 2; ++n) {
;             const size_t idx = (size_t)row * 1024 + u.pn * 256 + 128 * bj + 32 * wc + 16 * n + 4 * fq;
;             const unsigned ga = *reinterpret_cast<const unsigned*>(reinterpret_cast<const unsigned char*>(p.ws + OFF_RA) + idx);
;             const unsigned gb = *reinterpret_cast<const unsigned*>(reinterpret_cast<const unsigned char*>(p.ws + OFF_RB) + idx);
	ds_read_b128 v[200:203], v171 offset:49152
	ds_read_b128 v[204:207], v171 offset:50176
	ds_read_b128 v[208:211], v171 offset:51200
	ds_read_b128 v[212:215], v171 offset:52224
	ds_read_b128 v[216:219], v171 offset:53248
	ds_read_b128 v[220:223], v171 offset:54272
	ds_read_b128 v[224:227], v171 offset:55296
	ds_read_b128 v[228:231], v171 offset:56320
	global_load_lds_dwordx4 v[18:19], off
	v_lshl_add_u64 v[18:19], v[156:157], 0, s[42:43]
	s_mov_b32 m0, s31
	s_nop 0
	global_load_lds_dwordx4 v[18:19], off
	s_barrier
	s_waitcnt lgkmcnt(0)
	s_setprio 1
	s_waitcnt lgkmcnt(0)
	v_mfma_f32_16x16x32_bf16 v[66:69], v[178:181], v[200:203], v[66:69]
	v_mfma_f32_16x16x32_bf16 v[62:65], v[192:195], v[200:203], v[62:65]
	v_mfma_f32_16x16x32_bf16 v[50:53], v[178:181], v[208:211], v[50:53]
	v_mfma_f32_16x16x32_bf16 v[46:49], v[192:195], v[208:211], v[46:49]
	v_mfma_f32_16x16x32_bf16 v[34:37], v[178:181], v[216:219], v[34:37]
	v_mfma_f32_16x16x32_bf16 v[30:33], v[192:195], v[216:219], v[30:33]
	v_mfma_f32_16x16x32_bf16 v[12:15], v[178:181], v[224:227], v[12:15]
	v_mfma_f32_16x16x32_bf16 v[8:11], v[192:195], v[224:227], v[8:11]
	v_mfma_f32_16x16x32_bf16 v[66:69], v[188:191], v[204:207], v[66:69]
	v_mfma_f32_16x16x32_bf16 v[62:65], v[196:199], v[204:207], v[62:65]
	v_mfma_f32_16x16x32_bf16 v[50:53], v[188:191], v[212:215], v[50:53]
	v_mfma_f32_16x16x32_bf16 v[46:49], v[196:199], v[212:215], v[46:49]
	v_mfma_f32_16x16x32_bf16 v[34:37], v[188:191], v[220:223], v[34:37]
	v_mfma_f32_16x16x32_bf16 v[30:33], v[196:199], v[220:223], v[30:33]
	v_mfma_f32_16x16x32_bf16 v[12:15], v[188:191], v[228:231], v[12:15]
	v_mfma_f32_16x16x32_bf16 v[8:11], v[196:199], v[228:231], v[8:11]
	s_setprio 0
	s_barrier
	s_add_u32 s16, s16, 0x40080
	s_addc_u32 s17, s17, 0
	s_add_i32 s18, s18, s23
	v_lshl_add_u64 v[18:19], s[16:17], 0, v[136:137]
	s_mov_b32 m0, s18
	s_nop 0
	global_load_lds_dwordx4 v[18:19], off
	v_lshl_add_u64 v[18:19], s[16:17], 0, v[134:135]
	s_add_i32 m0, s18, 0x2000
	s_nop 0
	global_load_lds_dwordx4 v[18:19], off
	s_waitcnt vmcnt(6)
	s_barrier
	s_setprio 1
	v_mfma_f32_16x16x32_bf16 v[58:61], v[232:235], v[200:203], v[58:61]
	v_mfma_f32_16x16x32_bf16 v[54:57], v[240:243], v[200:203], v[54:57]
	v_mfma_f32_16x16x32_bf16 v[42:45], v[232:235], v[208:211], v[42:45]
	v_mfma_f32_16x16x32_bf16 v[38:41], v[240:243], v[208:211], v[38:41]
	v_mfma_f32_16x16x32_bf16 v[26:29], v[232:235], v[216:219], v[26:29]
	v_mfma_f32_16x16x32_bf16 v[22:25], v[240:243], v[216:219], v[22:25]
	v_mfma_f32_16x16x32_bf16 v[4:7], v[232:235], v[224:227], v[4:7]
	v_mfma_f32_16x16x32_bf16 v[0:3], v[240:243], v[224:227], v[0:3]
	v_mfma_f32_16x16x32_bf16 v[58:61], v[236:239], v[204:207], v[58:61]
	v_mfma_f32_16x16x32_bf16 v[54:57], v[244:247], v[204:207], v[54:57]
	v_mfma_f32_16x16x32_bf16 v[42:45], v[236:239], v[212:215], v[42:45]
	v_mfma_f32_16x16x32_bf16 v[38:41], v[244:247], v[212:215], v[38:41]
	v_mfma_f32_16x16x32_bf16 v[26:29], v[236:239], v[220:223], v[26:29]
	v_mfma_f32_16x16x32_bf16 v[22:25], v[244:247], v[220:223], v[22:25]
	v_mfma_f32_16x16x32_bf16 v[4:7], v[236:239], v[228:231], v[4:7]
	v_mfma_f32_16x16x32_bf16 v[0:3], v[244:247], v[228:231], v[0:3]
	s_setprio 0
	s_add_i32 s41, s41, 2
	s_add_u32 s14, s14, 0x100
	s_addc_u32 s15, s15, 0
	s_cmp_gt_u32 s41, 13
	s_barrier
	s_cbranch_scc1 .LBB0_2731
.LBB0_2736:
	s_cmpk_lg_i32 s14, 0x400
	s_cbranch_scc1 .LBB0_2735
	v_lshl_add_u32 v16, v148, 10, v150
	s_add_u32 s56, s46, 0x0
	s_addc_u32 s57, s47, 0
	s_add_u32 s58, s48, 0x0
	s_addc_u32 s59, s49, 0
	global_load_dword v186, v16, s[56:57]
	global_load_dword v187, v16, s[58:59]
	global_load_dword v188, v16, s[56:57] offset:16
	global_load_dword v189, v16, s[58:59] offset:16
	global_load_dword v190, v16, s[56:57] offset:128
	global_load_dword v191, v16, s[58:59] offset:128
	global_load_dword v192, v16, s[56:57] offset:144
	global_load_dword v193, v16, s[58:59] offset:144
	s_add_u32 s60, s46, 0x4000
	s_addc_u32 s61, s47, 0
	s_add_u32 s62, s48, 0x4000
	s_addc_u32 s63, s49, 0
	global_load_dword v194, v16, s[60:61]
	global_load_dword v195, v16, s[62:63]
	global_load_dword v196, v16, s[60:61] offset:16
	global_load_dword v197, v16, s[62:63] offset:16
	global_load_dword v198, v16, s[60:61] offset:128
	global_load_dword v199, v16, s[62:63] offset:128
	global_load_dword v200, v16, s[60:61] offset:144
	global_load_dword v201, v16, s[62:63] offset:144
	s_add_u32 s56, s46, 0x8000
	s_addc_u32 s57, s47, 0
	s_add_u32 s58, s48, 0x8000
	s_addc_u32 s59, s49, 0
	global_load_dword v202, v16, s[56:57]
	global_load_dword v203, v16, s[58:59]
	global_load_dword v204, v16, s[56:57] offset:16
	global_load_dword v205, v16, s[58:59] offset:16
	global_load_dword v206, v16, s[56:57] offset:128
	global_load_dword v207, v16, s[58:59] offset:128
	global_load_dword v208, v16, s[56:57] offset:144
	global_load_dword v209, v16, s[58:59] offset:144
	s_add_u32 s60, s46, 0xc000
	s_addc_u32 s61, s47, 0
	s_add_u32 s62, s48, 0xc000
	s_addc_u32 s63, s49, 0
	global_load_dword v210, v16, s[60:61]
	global_load_dword v211, v16, s[62:63]
	global_load_dword v212, v16, s[60:61] offset:16
	global_load_dword v213, v16, s[62:63] offset:16
	global_load_dword v214, v16, s[60:61] offset:128
	global_load_dword v215, v16, s[62:63] offset:128
	global_load_dword v216, v16, s[60:61] offset:144
	global_load_dword v217, v16, s[62:63] offset:144
	s_add_u32 s56, s46, 0x20000
	s_addc_u32 s57, s47, 0
	s_add_u32 s58, s48, 0x20000
	s_addc_u32 s59, s49, 0
	global_load_dword v218, v16, s[56:57]
	global_load_dword v219, v16, s[58:59]
	global_load_dword v220, v16, s[56:57] offset:16
	global_load_dword v221, v16, s[58:59] offset:16
	global_load_dword v222, v16, s[56:57] offset:128
	global_load_dword v223, v16, s[58:59] offset:128
	global_load_dword v224, v16, s[56:57] offset:144
	global_load_dword v225, v16, s[58:59] offset:144
	s_add_u32 s60, s46, 0x24000
	s_addc_u32 s61, s47, 0
	s_add_u32 s62, s48, 0x24000
	s_addc_u32 s63, s49, 0
	global_load_dword v226, v16, s[60:61]
	global_load_dword v227, v16, s[62:63]
	global_load_dword v228, v16, s[60:61] offset:16
	global_load_dword v229, v16, s[62:63] offset:16
	global_load_dword v230, v16, s[60:61] offset:128
	global_load_dword v231, v16, s[62:63] offset:128
	global_load_dword v232, v16, s[60:61] offset:144
	global_load_dword v233, v16, s[62:63] offset:144
	s_waitcnt vmcnt(46)
;   DI void mid(f32x4 (&acc)[2][2][4][2], const pg8::Unit& u, int wr, int wc, int fr, int fq) const {
;     ...
;             const unsigned gb = *reinterpret_cast<const unsigned*>(reinterpret_cast<const unsigned char*>(p.ws + OFF_RB) + idx);
; #pragma unroll
;             for (int j = 0; j < 4; ++j) {
;               const unsigned a8 = (ga >> (8 * j)) & 255u, b8 = (gb >> (8 * j)) & 255u;
;               acc[ai][bj][m][n][j] *= (float)a8 * __builtin_amdgcn_rcpf((float)(b8 > 1u ? b8 : 1u));
;             }
	v_max_u32_sdwa v154, v187, v182 dst_sel:DWORD dst_unused:UNUSED_PAD src0_sel:BYTE_0 src1_sel:DWORD
	v_max_u32_sdwa v155, v187, v182 dst_sel:DWORD dst_unused:UNUSED_PAD src0_sel:BYTE_1 src1_sel:DWORD
	v_max_u32_sdwa v156, v187, v182 dst_sel:DWORD dst_unused:UNUSED_PAD src0_sel:BYTE_2 src1_sel:DWORD
	v_max_u32_sdwa v157, v187, v182 dst_sel:DWORD dst_unused:UNUSED_PAD src0_sel:BYTE_3 src1_sel:DWORD
	v_cvt_f32_ubyte0_e32 v154, v154
	v_cvt_f32_ubyte0_e32 v155, v155
	v_cvt_f32_ubyte0_e32 v156, v156
	v_cvt_f32_ubyte0_e32 v157, v157
	v_rcp_iflag_f32_e32 v154, v154
	v_rcp_iflag_f32_e32 v155, v155
	v_rcp_iflag_f32_e32 v156, v156
	v_rcp_iflag_f32_e32 v157, v157
	v_cvt_f32_ubyte0_e32 v178, v186
	v_cvt_f32_ubyte1_e32 v179, v186
	v_cvt_f32_ubyte2_e32 v180, v186
	v_cvt_f32_ubyte3_e32 v181, v186
	s_add_u32 s56, s46, 0x28000
	s_addc_u32 s57, s47, 0
	s_add_u32 s58, s48, 0x28000
	s_addc_u32 s59, s49, 0
	global_load_dword v186, v16, s[56:57]
	global_load_dword v187, v16, s[58:59]
	v_pk_mul_f32 v[154:155], v[154:155], v[178:179]
	v_pk_mul_f32 v[156:157], v[156:157], v[180:181]
	v_pk_mul_f32 v[130:131], v[130:131], v[154:155]
	v_pk_mul_f32 v[132:133], v[132:133], v[156:157]
	s_waitcnt vmcnt(46)
	v_max_u32_sdwa v154, v189, v182 dst_sel:DWORD dst_unused:UNUSED_PAD src0_sel:BYTE_0 src1_sel:DWORD
	v_max_u32_sdwa v155, v189, v182 dst_sel:DWORD dst_unused:UNUSED_PAD src0_sel:BYTE_1 src1_sel:DWORD
	v_max_u32_sdwa v156, v189, v182 dst_sel:DWORD dst_unused:UNUSED_PAD src0_sel:BYTE_2 src1_sel:DWORD
	v_max_u32_sdwa v157, v189, v182 dst_sel:DWORD dst_unused:UNUSED_PAD src0_sel:BYTE_3 src1_sel:DWORD
	v_cvt_f32_ubyte0_e32 v154, v154
	v_cvt_f32_ubyte0_e32 v155, v155
	v_cvt_f32_ubyte0_e32 v156, v156
	v_cvt_f32_ubyte0_e32 v157, v157
	v_rcp_iflag_f32_e32 v154, v154
	v_rcp_iflag_f32_e32 v155, v155
	v_rcp_iflag_f32_e32 v156, v156
	v_rcp_iflag_f32_e32 v157, v157
	v_cvt_f32_ubyte0_e32 v178, v188
	v_cvt_f32_ubyte1_e32 v179, v188
	v_cvt_f32_ubyte2_e32 v180, v188
	v_cvt_f32_ubyte3_e32 v181, v188
	global_load_dword v188, v16, s[56:57] offset:16
	global_load_dword v189, v16, s[58:59] offset:16
	v_pk_mul_f32 v[154:155], v[154:155], v[178:179]
	v_pk_mul_f32 v[156:157], v[156:157], v[180:181]
	v_pk_mul_f32 v[126:127], v[126:127], v[154:155]
	v_pk_mul_f32 v[128:129], v[128:129], v[156:157]
	s_waitcnt vmcnt(46)
	v_max_u32_sdwa v154, v191, v182 dst_sel:DWORD dst_unused:UNUSED_PAD src0_sel:BYTE_0 src1_sel:DWORD
	v_max_u32_sdwa v155, v191, v182 dst_sel:DWORD dst_unused:UNUSED_PAD src0_sel:BYTE_1 src1_sel:DWORD
	v_max_u32_sdwa v156, v191, v182 dst_sel:DWORD dst_unused:UNUSED_PAD src0_sel:BYTE_2 src1_sel:DWORD
	v_max_u32_sdwa v157, v191, v182 dst_sel:DWORD dst_unused:UNUSED_PAD src0_sel:BYTE_3 src1_sel:DWORD
	v_cvt_f32_ubyte0_e32 v154, v154
	v_cvt_f32_ubyte0_e32 v155, v155
	v_cvt_f32_ubyte0_e32 v156, v156
	v_cvt_f32_ubyte0_e32 v157, v157
	v_rcp_iflag_f32_e32 v154, v154
	v_rcp_iflag_f32_e32 v155, v155
	v_rcp_iflag_f32_e32 v156, v156
	v_rcp_iflag_f32_e32 v157, v157
	v_cvt_f32_ubyte0_e32 v178, v190
	v_cvt_f32_ubyte1_e32 v179, v190
	v_cvt_f32_ubyte2_e32 v180, v190
	v_cvt_f32_ubyte3_e32 v181, v190
	global_load_dword v190, v16, s[56:57] offset:128
	global_load_dword v191, v16, s[58:59] offset:128
	v_pk_mul_f32 v[154:155], v[154:155], v[178:179]
	v_pk_mul_f32 v[156:157], v[156:157], v[180:181]
	v_pk_mul_f32 v[122:123], v[122:123], v[154:155]
	v_pk_mul_f32 v[124:125], v[124:125], v[156:157]
	s_waitcnt vmcnt(46)
	v_max_u32_sdwa v154, v193, v182 dst_sel:DWORD dst_unused:UNUSED_PAD src0_sel:BYTE_0 src1_sel:DWORD
	v_max_u32_sdwa v155, v193, v182 dst_sel:DWORD dst_unused:UNUSED_PAD src0_sel:BYTE_1 src1_sel:DWORD
	v_max_u32_sdwa v156, v193, v182 dst_sel:DWORD dst_unused:UNUSED_PAD src0_sel:BYTE_2 src1_sel:DWORD
	v_max_u32_sdwa v157, v193, v182 dst_sel:DWORD dst_unused:UNUSED_PAD src0_sel:BYTE_3 src1_sel:DWORD
	v_cvt_f32_ubyte0_e32 v154, v154
	v_cvt_f32_ubyte0_e32 v155, v155
	v_cvt_f32_ubyte0_e32 v156, v156
	v_cvt_f32_ubyte0_e32 v157, v157
	v_rcp_iflag_f32_e32 v154, v154
	v_rcp_iflag_f32_e32 v155, v155
	v_rcp_iflag_f32_e32 v156, v156
	v_rcp_iflag_f32_e32 v157, v157
	v_cvt_f32_ubyte0_e32 v178, v192
	v_cvt_f32_ubyte1_e32 v179, v192
	v_cvt_f32_ubyte2_e32 v180, v192
	v_cvt_f32_ubyte3_e32 v181, v192
	global_load_dword v192, v16, s[56:57] offset:144
	global_load_dword v193, v16, s[58:59] offset:144
	v_pk_mul_f32 v[154:155], v[154:155], v[178:179]
	v_pk_mul_f32 v[156:157], v[156:157], v[180:181]
	v_pk_mul_f32 v[118:119], v[118:119], v[154:155]
	v_pk_mul_f32 v[120:121], v[120:121], v[156:157]
	s_waitcnt vmcnt(46)
	v_max_u32_sdwa v154, v195, v182 dst_sel:DWORD dst_unused:UNUSED_PAD src0_sel:BYTE_0 src1_sel:DWORD
	v_max_u32_sdwa v155, v195, v182 dst_sel:DWORD dst_unused:UNUSED_PAD src0_sel:BYTE_1 src1_sel:DWORD
	v_max_u32_sdwa v156, v195, v182 dst_sel:DWORD dst_unused:UNUSED_PAD src0_sel:BYTE_2 src1_sel:DWORD
	v_max_u32_sdwa v157, v195, v182 dst_sel:DWORD dst_unused:UNUSED_PAD src0_sel:BYTE_3 src1_sel:DWORD
	v_cvt_f32_ubyte0_e32 v154, v154
	v_cvt_f32_ubyte0_e32 v155, v155
	v_cvt_f32_ubyte0_e32 v156, v156
	v_cvt_f32_ubyte0_e32 v157, v157
	v_rcp_iflag_f32_e32 v154, v154
	v_rcp_iflag_f32_e32 v155, v155
	v_rcp_iflag_f32_e32 v156, v156
	v_rcp_iflag_f32_e32 v157, v157
	v_cvt_f32_ubyte0_e32 v178, v194
	v_cvt_f32_ubyte1_e32 v179, v194
	v_cvt_f32_ubyte2_e32 v180, v194
	v_cvt_f32_ubyte3_e32 v181, v194
	s_add_u32 s60, s46, 0x2c000
	s_addc_u32 s61, s47, 0
	s_add_u32 s62, s48, 0x2c000
	s_addc_u32 s63, s49, 0
	global_load_dword v194, v16, s[60:61]
	global_load_dword v195, v16, s[62:63]
	v_pk_mul_f32 v[154:155], v[154:155], v[178:179]
	v_pk_mul_f32 v[156:157], v[156:157], v[180:181]
	v_pk_mul_f32 v[114:115], v[114:115], v[154:155]
	v_pk_mul_f32 v[116:117], v[116:117], v[156:157]
	s_waitcnt vmcnt(46)
;   DI void mid(f32x4 (&acc)[2][2][4][2], const pg8::Unit& u, int wr, int wc, int fr, int fq) const {
;     ...
;             const unsigned gb = *reinterpret_cast<const unsigned*>(reinterpret_cast<const unsigned char*>(p.ws + OFF_RB) + idx);
; #pragma unroll
;             for (int j = 0; j < 4; ++j) {
;               const unsigned a8 = (ga >> (8 * j)) & 255u, b8 = (gb >> (8 * j)) & 255u;
;               acc[ai][bj][m][n][j] *= (float)a8 * __builtin_amdgcn_rcpf((float)(b8 > 1u ? b8 : 1u));
;             }
	v_max_u32_sdwa v154, v197, v182 dst_sel:DWORD dst_unused:UNUSED_PAD src0_sel:BYTE_0 src1_sel:DWORD
	v_max_u32_sdwa v155, v197, v182 dst_sel:DWORD dst_unused:UNUSED_PAD src0_sel:BYTE_1 src1_sel:DWORD
	v_max_u32_sdwa v156, v197, v182 dst_sel:DWORD dst_unused:UNUSED_PAD src0_sel:BYTE_2 src1_sel:DWORD
	v_max_u32_sdwa v157, v197, v182 dst_sel:DWORD dst_unused:UNUSED_PAD src0_sel:BYTE_3 src1_sel:DWORD
	v_cvt_f32_ubyte0_e32 v154, v154
	v_cvt_f32_ubyte0_e32 v155, v155
	v_cvt_f32_ubyte0_e32 v156, v156
	v_cvt_f32_ubyte0_e32 v157, v157
	v_rcp_iflag_f32_e32 v154, v154
	v_rcp_iflag_f32_e32 v155, v155
	v_rcp_iflag_f32_e32 v156, v156
	v_rcp_iflag_f32_e32 v157, v157
	v_cvt_f32_ubyte0_e32 v178, v196
	v_cvt_f32_ubyte1_e32 v179, v196
	v_cvt_f32_ubyte2_e32 v180, v196
	v_cvt_f32_ubyte3_e32 v181, v196
	global_load_dword v196, v16, s[60:61] offset:16
	global_load_dword v197, v16, s[62:63] offset:16
	v_pk_mul_f32 v[154:155], v[154:155], v[178:179]
	v_pk_mul_f32 v[156:157], v[156:157], v[180:181]
	v_pk_mul_f32 v[110:111], v[110:111], v[154:155]
	v_pk_mul_f32 v[112:113], v[112:113], v[156:157]
	s_waitcnt vmcnt(46)
	v_max_u32_sdwa v154, v199, v182 dst_sel:DWORD dst_unused:UNUSED_PAD src0_sel:BYTE_0 src1_sel:DWORD
	v_max_u32_sdwa v155, v199, v182 dst_sel:DWORD dst_unused:UNUSED_PAD src0_sel:BYTE_1 src1_sel:DWORD
	v_max_u32_sdwa v156, v199, v182 dst_sel:DWORD dst_unused:UNUSED_PAD src0_sel:BYTE_2 src1_sel:DWORD
	v_max_u32_sdwa v157, v199, v182 dst_sel:DWORD dst_unused:UNUSED_PAD src0_sel:BYTE_3 src1_sel:DWORD
	v_cvt_f32_ubyte0_e32 v154, v154
	v_cvt_f32_ubyte0_e32 v155, v155
	v_cvt_f32_ubyte0_e32 v156, v156
	v_cvt_f32_ubyte0_e32 v157, v157
	v_rcp_iflag_f32_e32 v154, v154
	v_rcp_iflag_f32_e32 v155, v155
	v_rcp_iflag_f32_e32 v156, v156
	v_rcp_iflag_f32_e32 v157, v157
	v_cvt_f32_ubyte0_e32 v178, v198
	v_cvt_f32_ubyte1_e32 v179, v198
	v_cvt_f32_ubyte2_e32 v180, v198
	v_cvt_f32_ubyte3_e32 v181, v198
	global_load_dword v198, v16, s[60:61] offset:128
	global_load_dword v199, v16, s[62:63] offset:128
	v_pk_mul_f32 v[154:155], v[154:155], v[178:179]
	v_pk_mul_f32 v[156:157], v[156:157], v[180:181]
	v_pk_mul_f32 v[106:107], v[106:107], v[154:155]
	v_pk_mul_f32 v[108:109], v[108:109], v[156:157]
	s_waitcnt vmcnt(46)
	v_max_u32_sdwa v154, v201, v182 dst_sel:DWORD dst_unused:UNUSED_PAD src0_sel:BYTE_0 src1_sel:DWORD
	v_max_u32_sdwa v155, v201, v182 dst_sel:DWORD dst_unused:UNUSED_PAD src0_sel:BYTE_1 src1_sel:DWORD
	v_max_u32_sdwa v156, v201, v182 dst_sel:DWORD dst_unused:UNUSED_PAD src0_sel:BYTE_2 src1_sel:DWORD
	v_max_u32_sdwa v157, v201, v182 dst_sel:DWORD dst_unused:UNUSED_PAD src0_sel:BYTE_3 src1_sel:DWORD
	v_cvt_f32_ubyte0_e32 v154, v154
	v_cvt_f32_ubyte0_e32 v155, v155
	v_cvt_f32_ubyte0_e32 v156, v156
	v_cvt_f32_ubyte0_e32 v157, v157
	v_rcp_iflag_f32_e32 v154, v154
	v_rcp_iflag_f32_e32 v155, v155
	v_rcp_iflag_f32_e32 v156, v156
	v_rcp_iflag_f32_e32 v157, v157
	v_cvt_f32_ubyte0_e32 v178, v200
	v_cvt_f32_ubyte1_e32 v179, v200
	v_cvt_f32_ubyte2_e32 v180, v200
	v_cvt_f32_ubyte3_e32 v181, v200
	global_load_dword v200, v16, s[60:61] offset:144
	global_load_dword v201, v16, s[62:63] offset:144
	v_pk_mul_f32 v[154:155], v[154:155], v[178:179]
	v_pk_mul_f32 v[156:157], v[156:157], v[180:181]
	v_pk_mul_f32 v[102:103], v[102:103], v[154:155]
	v_pk_mul_f32 v[104:105], v[104:105], v[156:157]
	s_waitcnt vmcnt(46)
	v_max_u32_sdwa v154, v203, v182 dst_sel:DWORD dst_unused:UNUSED_PAD src0_sel:BYTE_0 src1_sel:DWORD
	v_max_u32_sdwa v155, v203, v182 dst_sel:DWORD dst_unused:UNUSED_PAD src0_sel:BYTE_1 src1_sel:DWORD
	v_max_u32_sdwa v156, v203, v182 dst_sel:DWORD dst_unused:UNUSED_PAD src0_sel:BYTE_2 src1_sel:DWORD
	v_max_u32_sdwa v157, v203, v182 dst_sel:DWORD dst_unused:UNUSED_PAD src0_sel:BYTE_3 src1_sel:DWORD
	v_cvt_f32_ubyte0_e32 v154, v154
	v_cvt_f32_ubyte0_e32 v155, v155
	v_cvt_f32_ubyte0_e32 v156, v156
	v_cvt_f32_ubyte0_e32 v157, v157
	v_rcp_iflag_f32_e32 v154, v154
	v_rcp_iflag_f32_e32 v155, v155
	v_rcp_iflag_f32_e32 v156, v156
	v_rcp_iflag_f32_e32 v157, v157
	v_cvt_f32_ubyte0_e32 v178, v202
	v_cvt_f32_ubyte1_e32 v179, v202
	v_cvt_f32_ubyte2_e32 v180, v202
	v_cvt_f32_ubyte3_e32 v181, v202
	v_pk_mul_f32 v[154:155], v[154:155], v[178:179]
	v_pk_mul_f32 v[156:157], v[156:157], v[180:181]
	v_pk_mul_f32 v[98:99], v[98:99], v[154:155]
	v_pk_mul_f32 v[100:101], v[100:101], v[156:157]
	s_waitcnt vmcnt(44)
	v_max_u32_sdwa v154, v205, v182 dst_sel:DWORD dst_unused:UNUSED_PAD src0_sel:BYTE_0 src1_sel:DWORD
	v_max_u32_sdwa v155, v205, v182 dst_sel:DWORD dst_unused:UNUSED_PAD src0_sel:BYTE_1 src1_sel:DWORD
	v_max_u32_sdwa v156, v205, v182 dst_sel:DWORD dst_unused:UNUSED_PAD src0_sel:BYTE_2 src1_sel:DWORD
	v_max_u32_sdwa v157, v205, v182 dst_sel:DWORD dst_unused:UNUSED_PAD src0_sel:BYTE_3 src1_sel:DWORD
	v_cvt_f32_ubyte0_e32 v154, v154
	v_cvt_f32_ubyte0_e32 v155, v155
	v_cvt_f32_ubyte0_e32 v156, v156
	v_cvt_f32_ubyte0_e32 v157, v157
	v_rcp_iflag_f32_e32 v154, v154
	v_rcp_iflag_f32_e32 v155, v155
	v_rcp_iflag_f32_e32 v156, v156
	v_rcp_iflag_f32_e32 v157, v157
	v_cvt_f32_ubyte0_e32 v178, v204
	v_cvt_f32_ubyte1_e32 v179, v204
	v_cvt_f32_ubyte2_e32 v180, v204
	v_cvt_f32_ubyte3_e32 v181, v204
	v_pk_mul_f32 v[154:155], v[154:155], v[178:179]
	v_pk_mul_f32 v[156:157], v[156:157], v[180:181]
	v_pk_mul_f32 v[94:95], v[94:95], v[154:155]
	v_pk_mul_f32 v[96:97], v[96:97], v[156:157]
	s_waitcnt vmcnt(42)
;   DI void mid(f32x4 (&acc)[2][2][4][2], const pg8::Unit& u, int wr, int wc, int fr, int fq) const {
;     ...
;             const unsigned gb = *reinterpret_cast<const unsigned*>(reinterpret_cast<const unsigned char*>(p.ws + OFF_RB) + idx);
; #pragma unroll
;             for (int j = 0; j < 4; ++j) {
;               const unsigned a8 = (ga >> (8 * j)) & 255u, b8 = (gb >> (8 * j)) & 255u;
;               acc[ai][bj][m][n][j] *= (float)a8 * __builtin_amdgcn_rcpf((float)(b8 > 1u ? b8 : 1u));
;             }
	v_max_u32_sdwa v154, v207, v182 dst_sel:DWORD dst_unused:UNUSED_PAD src0_sel:BYTE_0 src1_sel:DWORD
	v_max_u32_sdwa v155, v207, v182 dst_sel:DWORD dst_unused:UNUSED_PAD src0_sel:BYTE_1 src1_sel:DWORD
	v_max_u32_sdwa v156, v207, v182 dst_sel:DWORD dst_unused:UNUSED_PAD src0_sel:BYTE_2 src1_sel:DWORD
	v_max_u32_sdwa v157, v207, v182 dst_sel:DWORD dst_unused:UNUSED_PAD src0_sel:BYTE_3 src1_sel:DWORD
	v_cvt_f32_ubyte0_e32 v154, v154
	v_cvt_f32_ubyte0_e32 v155, v155
	v_cvt_f32_ubyte0_e32 v156, v156
	v_cvt_f32_ubyte0_e32 v157, v157
	v_rcp_iflag_f32_e32 v154, v154
	v_rcp_iflag_f32_e32 v155, v155
	v_rcp_iflag_f32_e32 v156, v156
	v_rcp_iflag_f32_e32 v157, v157
	v_cvt_f32_ubyte0_e32 v178, v206
	v_cvt_f32_ubyte1_e32 v179, v206
	v_cvt_f32_ubyte2_e32 v180, v206
	v_cvt_f32_ubyte3_e32 v181, v206
	v_pk_mul_f32 v[154:155], v[154:155], v[178:179]
	v_pk_mul_f32 v[156:157], v[156:157], v[180:181]
	v_pk_mul_f32 v[90:91], v[90:91], v[154:155]
	v_pk_mul_f32 v[92:93], v[92:93], v[156:157]
	s_waitcnt vmcnt(40)
	v_max_u32_sdwa v154, v209, v182 dst_sel:DWORD dst_unused:UNUSED_PAD src0_sel:BYTE_0 src1_sel:DWORD
	v_max_u32_sdwa v155, v209, v182 dst_sel:DWORD dst_unused:UNUSED_PAD src0_sel:BYTE_1 src1_sel:DWORD
	v_max_u32_sdwa v156, v209, v182 dst_sel:DWORD dst_unused:UNUSED_PAD src0_sel:BYTE_2 src1_sel:DWORD
	v_max_u32_sdwa v157, v209, v182 dst_sel:DWORD dst_unused:UNUSED_PAD src0_sel:BYTE_3 src1_sel:DWORD
	v_cvt_f32_ubyte0_e32 v154, v154
	v_cvt_f32_ubyte0_e32 v155, v155
	v_cvt_f32_ubyte0_e32 v156, v156
	v_cvt_f32_ubyte0_e32 v157, v157
	v_rcp_iflag_f32_e32 v154, v154
	v_rcp_iflag_f32_e32 v155, v155
	v_rcp_iflag_f32_e32 v156, v156
	v_rcp_iflag_f32_e32 v157, v157
	v_cvt_f32_ubyte0_e32 v178, v208
	v_cvt_f32_ubyte1_e32 v179, v208
	v_cvt_f32_ubyte2_e32 v180, v208
	v_cvt_f32_ubyte3_e32 v181, v208
	v_pk_mul_f32 v[154:155], v[154:155], v[178:179]
	v_pk_mul_f32 v[156:157], v[156:157], v[180:181]
	v_pk_mul_f32 v[86:87], v[86:87], v[154:155]
	v_pk_mul_f32 v[88:89], v[88:89], v[156:157]
	s_waitcnt vmcnt(38)
	v_max_u32_sdwa v154, v211, v182 dst_sel:DWORD dst_unused:UNUSED_PAD src0_sel:BYTE_0 src1_sel:DWORD
	v_max_u32_sdwa v155, v211, v182 dst_sel:DWORD dst_unused:UNUSED_PAD src0_sel:BYTE_1 src1_sel:DWORD
	v_max_u32_sdwa v156, v211, v182 dst_sel:DWORD dst_unused:UNUSED_PAD src0_sel:BYTE_2 src1_sel:DWORD
	v_max_u32_sdwa v157, v211, v182 dst_sel:DWORD dst_unused:UNUSED_PAD src0_sel:BYTE_3 src1_sel:DWORD
	v_cvt_f32_ubyte0_e32 v154, v154
	v_cvt_f32_ubyte0_e32 v155, v155
	v_cvt_f32_ubyte0_e32 v156, v156
	v_cvt_f32_ubyte0_e32 v157, v157
	v_rcp_iflag_f32_e32 v154, v154
	v_rcp_iflag_f32_e32 v155, v155
	v_rcp_iflag_f32_e32 v156, v156
	v_rcp_iflag_f32_e32 v157, v157
	v_cvt_f32_ubyte0_e32 v178, v210
	v_cvt_f32_ubyte1_e32 v179, v210
	v_cvt_f32_ubyte2_e32 v180, v210
	v_cvt_f32_ubyte3_e32 v181, v210
	v_pk_mul_f32 v[154:155], v[154:155], v[178:179]
	v_pk_mul_f32 v[156:157], v[156:157], v[180:181]
	v_pk_mul_f32 v[82:83], v[82:83], v[154:155]
	v_pk_mul_f32 v[84:85], v[84:85], v[156:157]
	s_waitcnt vmcnt(36)
	v_max_u32_sdwa v154, v213, v182 dst_sel:DWORD dst_unused:UNUSED_PAD src0_sel:BYTE_0 src1_sel:DWORD
	v_max_u32_sdwa v155, v213, v182 dst_sel:DWORD dst_unused:UNUSED_PAD src0_sel:BYTE_1 src1_sel:DWORD
	v_max_u32_sdwa v156, v213, v182 dst_sel:DWORD dst_unused:UNUSED_PAD src0_sel:BYTE_2 src1_sel:DWORD
	v_max_u32_sdwa v157, v213, v182 dst_sel:DWORD dst_unused:UNUSED_PAD src0_sel:BYTE_3 src1_sel:DWORD
	v_cvt_f32_ubyte0_e32 v154, v154
	v_cvt_f32_ubyte0_e32 v155, v155
	v_cvt_f32_ubyte0_e32 v156, v156
	v_cvt_f32_ubyte0_e32 v157, v157
	v_rcp_iflag_f32_e32 v154, v154
	v_rcp_iflag_f32_e32 v155, v155
	v_rcp_iflag_f32_e32 v156, v156
	v_rcp_iflag_f32_e32 v157, v157
	v_cvt_f32_ubyte0_e32 v178, v212
	v_cvt_f32_ubyte1_e32 v179, v212
	v_cvt_f32_ubyte2_e32 v180, v212
	v_cvt_f32_ubyte3_e32 v181, v212
	v_pk_mul_f32 v[154:155], v[154:155], v[178:179]
	v_pk_mul_f32 v[156:157], v[156:157], v[180:181]
	v_pk_mul_f32 v[78:79], v[78:79], v[154:155]
	v_pk_mul_f32 v[80:81], v[80:81], v[156:157]
	s_waitcnt vmcnt(34)
	v_max_u32_sdwa v154, v215, v182 dst_sel:DWORD dst_unused:UNUSED_PAD src0_sel:BYTE_0 src1_sel:DWORD
	v_max_u32_sdwa v155, v215, v182 dst_sel:DWORD dst_unused:UNUSED_PAD src0_sel:BYTE_1 src1_sel:DWORD
	v_max_u32_sdwa v156, v215, v182 dst_sel:DWORD dst_unused:UNUSED_PAD src0_sel:BYTE_2 src1_sel:DWORD
	v_max_u32_sdwa v157, v215, v182 dst_sel:DWORD dst_unused:UNUSED_PAD src0_sel:BYTE_3 src1_sel:DWORD
	v_cvt_f32_ubyte0_e32 v154, v154
	v_cvt_f32_ubyte0_e32 v155, v155
	v_cvt_f32_ubyte0_e32 v156, v156
	v_cvt_f32_ubyte0_e32 v157, v157
	v_rcp_iflag_f32_e32 v154, v154
	v_rcp_iflag_f32_e32 v155, v155
	v_rcp_iflag_f32_e32 v156, v156
	v_rcp_iflag_f32_e32 v157, v157
	v_cvt_f32_ubyte0_e32 v178, v214
	v_cvt_f32_ubyte1_e32 v179, v214
	v_cvt_f32_ubyte2_e32 v180, v214
	v_cvt_f32_ubyte3_e32 v181, v214
	v_pk_mul_f32 v[154:155], v[154:155], v[178:179]
	v_pk_mul_f32 v[156:157], v[156:157], v[180:181]
	v_pk_mul_f32 v[74:75], v[74:75], v[154:155]
	v_pk_mul_f32 v[76:77], v[76:77], v[156:157]
	s_waitcnt vmcnt(32)
	v_max_u32_sdwa v154, v217, v182 dst_sel:DWORD dst_unused:UNUSED_PAD src0_sel:BYTE_0 src1_sel:DWORD
	v_max_u32_sdwa v155, v217, v182 dst_sel:DWORD dst_unused:UNUSED_PAD src0_sel:BYTE_1 src1_sel:DWORD
	v_max_u32_sdwa v156, v217, v182 dst_sel:DWORD dst_unused:UNUSED_PAD src0_sel:BYTE_2 src1_sel:DWORD
	v_max_u32_sdwa v157, v217, v182 dst_sel:DWORD dst_unused:UNUSED_PAD src0_sel:BYTE_3 src1_sel:DWORD
	v_cvt_f32_ubyte0_e32 v154, v154
	v_cvt_f32_ubyte0_e32 v155, v155
	v_cvt_f32_ubyte0_e32 v156, v156
	v_cvt_f32_ubyte0_e32 v157, v157
	v_rcp_iflag_f32_e32 v154, v154
	v_rcp_iflag_f32_e32 v155, v155
	v_rcp_iflag_f32_e32 v156, v156
	v_rcp_iflag_f32_e32 v157, v157
	v_cvt_f32_ubyte0_e32 v178, v216
	v_cvt_f32_ubyte1_e32 v179, v216
	v_cvt_f32_ubyte2_e32 v180, v216
	v_cvt_f32_ubyte3_e32 v181, v216
	v_pk_mul_f32 v[154:155], v[154:155], v[178:179]
	v_pk_mul_f32 v[156:157], v[156:157], v[180:181]
	v_pk_mul_f32 v[70:71], v[70:71], v[154:155]
	v_pk_mul_f32 v[72:73], v[72:73], v[156:157]
	s_waitcnt vmcnt(30)
;   DI void mid(f32x4 (&acc)[2][2][4][2], const pg8::Unit& u, int wr, int wc, int fr, int fq) const {
;     ...
;             const unsigned gb = *reinterpret_cast<const unsigned*>(reinterpret_cast<const unsigned char*>(p.ws + OFF_RB) + idx);
; #pragma unroll
;             for (int j = 0; j < 4; ++j) {
;               const unsigned a8 = (ga >> (8 * j)) & 255u, b8 = (gb >> (8 * j)) & 255u;
;               acc[ai][bj][m][n][j] *= (float)a8 * __builtin_amdgcn_rcpf((float)(b8 > 1u ? b8 : 1u));
;             }
	v_max_u32_sdwa v154, v219, v182 dst_sel:DWORD dst_unused:UNUSED_PAD src0_sel:BYTE_0 src1_sel:DWORD
	v_max_u32_sdwa v155, v219, v182 dst_sel:DWORD dst_unused:UNUSED_PAD src0_sel:BYTE_1 src1_sel:DWORD
	v_max_u32_sdwa v156, v219, v182 dst_sel:DWORD dst_unused:UNUSED_PAD src0_sel:BYTE_2 src1_sel:DWORD
	v_max_u32_sdwa v157, v219, v182 dst_sel:DWORD dst_unused:UNUSED_PAD src0_sel:BYTE_3 src1_sel:DWORD
	v_cvt_f32_ubyte0_e32 v154, v154
	v_cvt_f32_ubyte0_e32 v155, v155
	v_cvt_f32_ubyte0_e32 v156, v156
	v_cvt_f32_ubyte0_e32 v157, v157
	v_rcp_iflag_f32_e32 v154, v154
	v_rcp_iflag_f32_e32 v155, v155
	v_rcp_iflag_f32_e32 v156, v156
	v_rcp_iflag_f32_e32 v157, v157
	v_cvt_f32_ubyte0_e32 v178, v218
	v_cvt_f32_ubyte1_e32 v179, v218
	v_cvt_f32_ubyte2_e32 v180, v218
	v_cvt_f32_ubyte3_e32 v181, v218
	v_pk_mul_f32 v[154:155], v[154:155], v[178:179]
	v_pk_mul_f32 v[156:157], v[156:157], v[180:181]
	v_pk_mul_f32 v[66:67], v[66:67], v[154:155]
	v_pk_mul_f32 v[68:69], v[68:69], v[156:157]
	s_waitcnt vmcnt(28)
	v_max_u32_sdwa v154, v221, v182 dst_sel:DWORD dst_unused:UNUSED_PAD src0_sel:BYTE_0 src1_sel:DWORD
	v_max_u32_sdwa v155, v221, v182 dst_sel:DWORD dst_unused:UNUSED_PAD src0_sel:BYTE_1 src1_sel:DWORD
	v_max_u32_sdwa v156, v221, v182 dst_sel:DWORD dst_unused:UNUSED_PAD src0_sel:BYTE_2 src1_sel:DWORD
	v_max_u32_sdwa v157, v221, v182 dst_sel:DWORD dst_unused:UNUSED_PAD src0_sel:BYTE_3 src1_sel:DWORD
	v_cvt_f32_ubyte0_e32 v154, v154
	v_cvt_f32_ubyte0_e32 v155, v155
	v_cvt_f32_ubyte0_e32 v156, v156
	v_cvt_f32_ubyte0_e32 v157, v157
	v_rcp_iflag_f32_e32 v154, v154
	v_rcp_iflag_f32_e32 v155, v155
	v_rcp_iflag_f32_e32 v156, v156
	v_rcp_iflag_f32_e32 v157, v157
	v_cvt_f32_ubyte0_e32 v178, v220
	v_cvt_f32_ubyte1_e32 v179, v220
	v_cvt_f32_ubyte2_e32 v180, v220
	v_cvt_f32_ubyte3_e32 v181, v220
	v_pk_mul_f32 v[154:155], v[154:155], v[178:179]
	v_pk_mul_f32 v[156:157], v[156:157], v[180:181]
	v_pk_mul_f32 v[62:63], v[62:63], v[154:155]
	v_pk_mul_f32 v[64:65], v[64:65], v[156:157]
	s_waitcnt vmcnt(26)
	v_max_u32_sdwa v154, v223, v182 dst_sel:DWORD dst_unused:UNUSED_PAD src0_sel:BYTE_0 src1_sel:DWORD
	v_max_u32_sdwa v155, v223, v182 dst_sel:DWORD dst_unused:UNUSED_PAD src0_sel:BYTE_1 src1_sel:DWORD
	v_max_u32_sdwa v156, v223, v182 dst_sel:DWORD dst_unused:UNUSED_PAD src0_sel:BYTE_2 src1_sel:DWORD
	v_max_u32_sdwa v157, v223, v182 dst_sel:DWORD dst_unused:UNUSED_PAD src0_sel:BYTE_3 src1_sel:DWORD
	v_cvt_f32_ubyte0_e32 v154, v154
	v_cvt_f32_ubyte0_e32 v155, v155
	v_cvt_f32_ubyte0_e32 v156, v156
	v_cvt_f32_ubyte0_e32 v157, v157
	v_rcp_iflag_f32_e32 v154, v154
	v_rcp_iflag_f32_e32 v155, v155
	v_rcp_iflag_f32_e32 v156, v156
	v_rcp_iflag_f32_e32 v157, v157
	v_cvt_f32_ubyte0_e32 v178, v222
	v_cvt_f32_ubyte1_e32 v179, v222
	v_cvt_f32_ubyte2_e32 v180, v222
	v_cvt_f32_ubyte3_e32 v181, v222
	v_pk_mul_f32 v[154:155], v[154:155], v[178:179]
	v_pk_mul_f32 v[156:157], v[156:157], v[180:181]
	v_pk_mul_f32 v[58:59], v[58:59], v[154:155]
	v_pk_mul_f32 v[60:61], v[60:61], v[156:157]
	s_waitcnt vmcnt(24)
	v_max_u32_sdwa v154, v225, v182 dst_sel:DWORD dst_unused:UNUSED_PAD src0_sel:BYTE_0 src1_sel:DWORD
	v_max_u32_sdwa v155, v225, v182 dst_sel:DWORD dst_unused:UNUSED_PAD src0_sel:BYTE_1 src1_sel:DWORD
	v_max_u32_sdwa v156, v225, v182 dst_sel:DWORD dst_unused:UNUSED_PAD src0_sel:BYTE_2 src1_sel:DWORD
	v_max_u32_sdwa v157, v225, v182 dst_sel:DWORD dst_unused:UNUSED_PAD src0_sel:BYTE_3 src1_sel:DWORD
	v_cvt_f32_ubyte0_e32 v154, v154
	v_cvt_f32_ubyte0_e32 v155, v155
	v_cvt_f32_ubyte0_e32 v156, v156
	v_cvt_f32_ubyte0_e32 v157, v157
	v_rcp_iflag_f32_e32 v154, v154
	v_rcp_iflag_f32_e32 v155, v155
	v_rcp_iflag_f32_e32 v156, v156
	v_rcp_iflag_f32_e32 v157, v157
	v_cvt_f32_ubyte0_e32 v178, v224
	v_cvt_f32_ubyte1_e32 v179, v224
	v_cvt_f32_ubyte2_e32 v180, v224
	v_cvt_f32_ubyte3_e32 v181, v224
	v_pk_mul_f32 v[154:155], v[154:155], v[178:179]
	v_pk_mul_f32 v[156:157], v[156:157], v[180:181]
	v_pk_mul_f32 v[54:55], v[54:55], v[154:155]
	v_pk_mul_f32 v[56:57], v[56:57], v[156:157]
	s_waitcnt vmcnt(22)
	v_max_u32_sdwa v154, v227, v182 dst_sel:DWORD dst_unused:UNUSED_PAD src0_sel:BYTE_0 src1_sel:DWORD
	v_max_u32_sdwa v155, v227, v182 dst_sel:DWORD dst_unused:UNUSED_PAD src0_sel:BYTE_1 src1_sel:DWORD
	v_max_u32_sdwa v156, v227, v182 dst_sel:DWORD dst_unused:UNUSED_PAD src0_sel:BYTE_2 src1_sel:DWORD
	v_max_u32_sdwa v157, v227, v182 dst_sel:DWORD dst_unused:UNUSED_PAD src0_sel:BYTE_3 src1_sel:DWORD
	v_cvt_f32_ubyte0_e32 v154, v154
	v_cvt_f32_ubyte0_e32 v155, v155
	v_cvt_f32_ubyte0_e32 v156, v156
	v_cvt_f32_ubyte0_e32 v157, v157
	v_rcp_iflag_f32_e32 v154, v154
	v_rcp_iflag_f32_e32 v155, v155
	v_rcp_iflag_f32_e32 v156, v156
	v_rcp_iflag_f32_e32 v157, v157
	v_cvt_f32_ubyte0_e32 v178, v226
	v_cvt_f32_ubyte1_e32 v179, v226
	v_cvt_f32_ubyte2_e32 v180, v226
	v_cvt_f32_ubyte3_e32 v181, v226
	v_pk_mul_f32 v[154:155], v[154:155], v[178:179]
	v_pk_mul_f32 v[156:157], v[156:157], v[180:181]
	v_pk_mul_f32 v[50:51], v[50:51], v[154:155]
	v_pk_mul_f32 v[52:53], v[52:53], v[156:157]
	s_waitcnt vmcnt(20)
	v_max_u32_sdwa v154, v229, v182 dst_sel:DWORD dst_unused:UNUSED_PAD src0_sel:BYTE_0 src1_sel:DWORD
	v_max_u32_sdwa v155, v229, v182 dst_sel:DWORD dst_unused:UNUSED_PAD src0_sel:BYTE_1 src1_sel:DWORD
	v_max_u32_sdwa v156, v229, v182 dst_sel:DWORD dst_unused:UNUSED_PAD src0_sel:BYTE_2 src1_sel:DWORD
	v_max_u32_sdwa v157, v229, v182 dst_sel:DWORD dst_unused:UNUSED_PAD src0_sel:BYTE_3 src1_sel:DWORD
	v_cvt_f32_ubyte0_e32 v154, v154
	v_cvt_f32_ubyte0_e32 v155, v155
	v_cvt_f32_ubyte0_e32 v156, v156
	v_cvt_f32_ubyte0_e32 v157, v157
	v_rcp_iflag_f32_e32 v154, v154
	v_rcp_iflag_f32_e32 v155, v155
	v_rcp_iflag_f32_e32 v156, v156
	v_rcp_iflag_f32_e32 v157, v157
	v_cvt_f32_ubyte0_e32 v178, v228
	v_cvt_f32_ubyte1_e32 v179, v228
	v_cvt_f32_ubyte2_e32 v180, v228
	v_cvt_f32_ubyte3_e32 v181, v228
	v_pk_mul_f32 v[154:155], v[154:155], v[178:179]
	v_pk_mul_f32 v[156:157], v[156:157], v[180:181]
	v_pk_mul_f32 v[46:47], v[46:47], v[154:155]
	v_pk_mul_f32 v[48:49], v[48:49], v[156:157]
	s_waitcnt vmcnt(18)
;   DI void mid(f32x4 (&acc)[2][2][4][2], const pg8::Unit& u, int wr, int wc, int fr, int fq) const {
;     ...
;             const unsigned gb = *reinterpret_cast<const unsigned*>(reinterpret_cast<const unsigned char*>(p.ws + OFF_RB) + idx);
; #pragma unroll
;             for (int j = 0; j < 4; ++j) {
;               const unsigned a8 = (ga >> (8 * j)) & 255u, b8 = (gb >> (8 * j)) & 255u;
;               acc[ai][bj][m][n][j] *= (float)a8 * __builtin_amdgcn_rcpf((float)(b8 > 1u ? b8 : 1u));
;             }
	v_max_u32_sdwa v154, v231, v182 dst_sel:DWORD dst_unused:UNUSED_PAD src0_sel:BYTE_0 src1_sel:DWORD
	v_max_u32_sdwa v155, v231, v182 dst_sel:DWORD dst_unused:UNUSED_PAD src0_sel:BYTE_1 src1_sel:DWORD
	v_max_u32_sdwa v156, v231, v182 dst_sel:DWORD dst_unused:UNUSED_PAD src0_sel:BYTE_2 src1_sel:DWORD
	v_max_u32_sdwa v157, v231, v182 dst_sel:DWORD dst_unused:UNUSED_PAD src0_sel:BYTE_3 src1_sel:DWORD
	v_cvt_f32_ubyte0_e32 v154, v154
	v_cvt_f32_ubyte0_e32 v155, v155
	v_cvt_f32_ubyte0_e32 v156, v156
	v_cvt_f32_ubyte0_e32 v157, v157
	v_rcp_iflag_f32_e32 v154, v154
	v_rcp_iflag_f32_e32 v155, v155
	v_rcp_iflag_f32_e32 v156, v156
	v_rcp_iflag_f32_e32 v157, v157
	v_cvt_f32_ubyte0_e32 v178, v230
	v_cvt_f32_ubyte1_e32 v179, v230
	v_cvt_f32_ubyte2_e32 v180, v230
	v_cvt_f32_ubyte3_e32 v181, v230
	v_pk_mul_f32 v[154:155], v[154:155], v[178:179]
	v_pk_mul_f32 v[156:157], v[156:157], v[180:181]
	v_pk_mul_f32 v[42:43], v[42:43], v[154:155]
	v_pk_mul_f32 v[44:45], v[44:45], v[156:157]
	s_waitcnt vmcnt(16)
	v_max_u32_sdwa v154, v233, v182 dst_sel:DWORD dst_unused:UNUSED_PAD src0_sel:BYTE_0 src1_sel:DWORD
	v_max_u32_sdwa v155, v233, v182 dst_sel:DWORD dst_unused:UNUSED_PAD src0_sel:BYTE_1 src1_sel:DWORD
	v_max_u32_sdwa v156, v233, v182 dst_sel:DWORD dst_unused:UNUSED_PAD src0_sel:BYTE_2 src1_sel:DWORD
	v_max_u32_sdwa v157, v233, v182 dst_sel:DWORD dst_unused:UNUSED_PAD src0_sel:BYTE_3 src1_sel:DWORD
	v_cvt_f32_ubyte0_e32 v154, v154
	v_cvt_f32_ubyte0_e32 v155, v155
	v_cvt_f32_ubyte0_e32 v156, v156
	v_cvt_f32_ubyte0_e32 v157, v157
	v_rcp_iflag_f32_e32 v154, v154
	v_rcp_iflag_f32_e32 v155, v155
	v_rcp_iflag_f32_e32 v156, v156
	v_rcp_iflag_f32_e32 v157, v157
	v_cvt_f32_ubyte0_e32 v178, v232
	v_cvt_f32_ubyte1_e32 v179, v232
	v_cvt_f32_ubyte2_e32 v180, v232
	v_cvt_f32_ubyte3_e32 v181, v232
	v_pk_mul_f32 v[154:155], v[154:155], v[178:179]
	v_pk_mul_f32 v[156:157], v[156:157], v[180:181]
	v_pk_mul_f32 v[38:39], v[38:39], v[154:155]
	v_pk_mul_f32 v[40:41], v[40:41], v[156:157]
	s_waitcnt vmcnt(14)
	v_max_u32_sdwa v154, v187, v182 dst_sel:DWORD dst_unused:UNUSED_PAD src0_sel:BYTE_0 src1_sel:DWORD
	v_max_u32_sdwa v155, v187, v182 dst_sel:DWORD dst_unused:UNUSED_PAD src0_sel:BYTE_1 src1_sel:DWORD
	v_max_u32_sdwa v156, v187, v182 dst_sel:DWORD dst_unused:UNUSED_PAD src0_sel:BYTE_2 src1_sel:DWORD
	v_max_u32_sdwa v157, v187, v182 dst_sel:DWORD dst_unused:UNUSED_PAD src0_sel:BYTE_3 src1_sel:DWORD
	v_cvt_f32_ubyte0_e32 v154, v154
	v_cvt_f32_ubyte0_e32 v155, v155
	v_cvt_f32_ubyte0_e32 v156, v156
	v_cvt_f32_ubyte0_e32 v157, v157
	v_rcp_iflag_f32_e32 v154, v154
	v_rcp_iflag_f32_e32 v155, v155
	v_rcp_iflag_f32_e32 v156, v156
	v_rcp_iflag_f32_e32 v157, v157
	v_cvt_f32_ubyte0_e32 v178, v186
	v_cvt_f32_ubyte1_e32 v179, v186
	v_cvt_f32_ubyte2_e32 v180, v186
	v_cvt_f32_ubyte3_e32 v181, v186
	v_pk_mul_f32 v[154:155], v[154:155], v[178:179]
	v_pk_mul_f32 v[156:157], v[156:157], v[180:181]
	v_pk_mul_f32 v[34:35], v[34:35], v[154:155]
	v_pk_mul_f32 v[36:37], v[36:37], v[156:157]
	s_waitcnt vmcnt(12)
	v_max_u32_sdwa v154, v189, v182 dst_sel:DWORD dst_unused:UNUSED_PAD src0_sel:BYTE_0 src1_sel:DWORD
	v_max_u32_sdwa v155, v189, v182 dst_sel:DWORD dst_unused:UNUSED_PAD src0_sel:BYTE_1 src1_sel:DWORD
	v_max_u32_sdwa v156, v189, v182 dst_sel:DWORD dst_unused:UNUSED_PAD src0_sel:BYTE_2 src1_sel:DWORD
	v_max_u32_sdwa v157, v189, v182 dst_sel:DWORD dst_unused:UNUSED_PAD src0_sel:BYTE_3 src1_sel:DWORD
	v_cvt_f32_ubyte0_e32 v154, v154
	v_cvt_f32_ubyte0_e32 v155, v155
	v_cvt_f32_ubyte0_e32 v156, v156
	v_cvt_f32_ubyte0_e32 v157, v157
	v_rcp_iflag_f32_e32 v154, v154
	v_rcp_iflag_f32_e32 v155, v155
	v_rcp_iflag_f32_e32 v156, v156
	v_rcp_iflag_f32_e32 v157, v157
	v_cvt_f32_ubyte0_e32 v178, v188
	v_cvt_f32_ubyte1_e32 v179, v188
	v_cvt_f32_ubyte2_e32 v180, v188
	v_cvt_f32_ubyte3_e32 v181, v188
	v_pk_mul_f32 v[154:155], v[154:155], v[178:179]
	v_pk_mul_f32 v[156:157], v[156:157], v[180:181]
	v_pk_mul_f32 v[30:31], v[30:31], v[154:155]
	v_pk_mul_f32 v[32:33], v[32:33], v[156:157]
	s_waitcnt vmcnt(10)
	v_max_u32_sdwa v154, v191, v182 dst_sel:DWORD dst_unused:UNUSED_PAD src0_sel:BYTE_0 src1_sel:DWORD
	v_max_u32_sdwa v155, v191, v182 dst_sel:DWORD dst_unused:UNUSED_PAD src0_sel:BYTE_1 src1_sel:DWORD
	v_max_u32_sdwa v156, v191, v182 dst_sel:DWORD dst_unused:UNUSED_PAD src0_sel:BYTE_2 src1_sel:DWORD
	v_max_u32_sdwa v157, v191, v182 dst_sel:DWORD dst_unused:UNUSED_PAD src0_sel:BYTE_3 src1_sel:DWORD
	v_cvt_f32_ubyte0_e32 v154, v154
	v_cvt_f32_ubyte0_e32 v155, v155
	v_cvt_f32_ubyte0_e32 v156, v156
	v_cvt_f32_ubyte0_e32 v157, v157
	v_rcp_iflag_f32_e32 v154, v154
	v_rcp_iflag_f32_e32 v155, v155
	v_rcp_iflag_f32_e32 v156, v156
	v_rcp_iflag_f32_e32 v157, v157
	v_cvt_f32_ubyte0_e32 v178, v190
	v_cvt_f32_ubyte1_e32 v179, v190
	v_cvt_f32_ubyte2_e32 v180, v190
	v_cvt_f32_ubyte3_e32 v181, v190
	v_pk_mul_f32 v[154:155], v[154:155], v[178:179]
	v_pk_mul_f32 v[156:157], v[156:157], v[180:181]
	v_pk_mul_f32 v[26:27], v[26:27], v[154:155]
	v_pk_mul_f32 v[28:29], v[28:29], v[156:157]
	s_waitcnt vmcnt(8)
;   DI void mid(f32x4 (&acc)[2][2][4][2], const pg8::Unit& u, int wr, int wc, int fr, int fq) const {
;     ...
;             const unsigned gb = *reinterpret_cast<const unsigned*>(reinterpret_cast<const unsigned char*>(p.ws + OFF_RB) + idx);
; #pragma unroll
;             for (int j = 0; j < 4; ++j) {
;               const unsigned a8 = (ga >> (8 * j)) & 255u, b8 = (gb >> (8 * j)) & 255u;
;               acc[ai][bj][m][n][j] *= (float)a8 * __builtin_amdgcn_rcpf((float)(b8 > 1u ? b8 : 1u));
;             }
;           }
;         asm volatile("" ::: "memory");
;       }
	v_max_u32_sdwa v154, v193, v182 dst_sel:DWORD dst_unused:UNUSED_PAD src0_sel:BYTE_0 src1_sel:DWORD
	v_max_u32_sdwa v155, v193, v182 dst_sel:DWORD dst_unused:UNUSED_PAD src0_sel:BYTE_1 src1_sel:DWORD
	v_max_u32_sdwa v156, v193, v182 dst_sel:DWORD dst_unused:UNUSED_PAD src0_sel:BYTE_2 src1_sel:DWORD
	v_max_u32_sdwa v157, v193, v182 dst_sel:DWORD dst_unused:UNUSED_PAD src0_sel:BYTE_3 src1_sel:DWORD
	v_cvt_f32_ubyte0_e32 v154, v154
	v_cvt_f32_ubyte0_e32 v155, v155
	v_cvt_f32_ubyte0_e32 v156, v156
	v_cvt_f32_ubyte0_e32 v157, v157
	v_rcp_iflag_f32_e32 v154, v154
	v_rcp_iflag_f32_e32 v155, v155
	v_rcp_iflag_f32_e32 v156, v156
	v_rcp_iflag_f32_e32 v157, v157
	v_cvt_f32_ubyte0_e32 v178, v192
	v_cvt_f32_ubyte1_e32 v179, v192
	v_cvt_f32_ubyte2_e32 v180, v192
	v_cvt_f32_ubyte3_e32 v181, v192
	v_pk_mul_f32 v[154:155], v[154:155], v[178:179]
	v_pk_mul_f32 v[156:157], v[156:157], v[180:181]
	v_pk_mul_f32 v[22:23], v[22:23], v[154:155]
	v_pk_mul_f32 v[24:25], v[24:25], v[156:157]
	s_waitcnt vmcnt(6)
	v_max_u32_sdwa v154, v195, v182 dst_sel:DWORD dst_unused:UNUSED_PAD src0_sel:BYTE_0 src1_sel:DWORD
	v_max_u32_sdwa v155, v195, v182 dst_sel:DWORD dst_unused:UNUSED_PAD src0_sel:BYTE_1 src1_sel:DWORD
	v_max_u32_sdwa v156, v195, v182 dst_sel:DWORD dst_unused:UNUSED_PAD src0_sel:BYTE_2 src1_sel:DWORD
	v_max_u32_sdwa v157, v195, v182 dst_sel:DWORD dst_unused:UNUSED_PAD src0_sel:BYTE_3 src1_sel:DWORD
	v_cvt_f32_ubyte0_e32 v154, v154
	v_cvt_f32_ubyte0_e32 v155, v155
	v_cvt_f32_ubyte0_e32 v156, v156
	v_cvt_f32_ubyte0_e32 v157, v157
	v_rcp_iflag_f32_e32 v154, v154
	v_rcp_iflag_f32_e32 v155, v155
	v_rcp_iflag_f32_e32 v156, v156
	v_rcp_iflag_f32_e32 v157, v157
	v_cvt_f32_ubyte0_e32 v178, v194
	v_cvt_f32_ubyte1_e32 v179, v194
	v_cvt_f32_ubyte2_e32 v180, v194
	v_cvt_f32_ubyte3_e32 v181, v194
	v_pk_mul_f32 v[154:155], v[154:155], v[178:179]
	v_pk_mul_f32 v[156:157], v[156:157], v[180:181]
	v_pk_mul_f32 v[12:13], v[12:13], v[154:155]
	v_pk_mul_f32 v[14:15], v[14:15], v[156:157]
	s_waitcnt vmcnt(4)
	v_max_u32_sdwa v154, v197, v182 dst_sel:DWORD dst_unused:UNUSED_PAD src0_sel:BYTE_0 src1_sel:DWORD
	v_max_u32_sdwa v155, v197, v182 dst_sel:DWORD dst_unused:UNUSED_PAD src0_sel:BYTE_1 src1_sel:DWORD
	v_max_u32_sdwa v156, v197, v182 dst_sel:DWORD dst_unused:UNUSED_PAD src0_sel:BYTE_2 src1_sel:DWORD
	v_max_u32_sdwa v157, v197, v182 dst_sel:DWORD dst_unused:UNUSED_PAD src0_sel:BYTE_3 src1_sel:DWORD
	v_cvt_f32_ubyte0_e32 v154, v154
	v_cvt_f32_ubyte0_e32 v155, v155
	v_cvt_f32_ubyte0_e32 v156, v156
	v_cvt_f32_ubyte0_e32 v157, v157
	v_rcp_iflag_f32_e32 v154, v154
	v_rcp_iflag_f32_e32 v155, v155
	v_rcp_iflag_f32_e32 v156, v156
	v_rcp_iflag_f32_e32 v157, v157
	v_cvt_f32_ubyte0_e32 v178, v196
	v_cvt_f32_ubyte1_e32 v179, v196
	v_cvt_f32_ubyte2_e32 v180, v196
	v_cvt_f32_ubyte3_e32 v181, v196
	v_pk_mul_f32 v[154:155], v[154:155], v[178:179]
	v_pk_mul_f32 v[156:157], v[156:157], v[180:181]
	v_pk_mul_f32 v[8:9], v[8:9], v[154:155]
	v_pk_mul_f32 v[10:11], v[10:11], v[156:157]
	s_waitcnt vmcnt(2)
	v_max_u32_sdwa v154, v199, v182 dst_sel:DWORD dst_unused:UNUSED_PAD src0_sel:BYTE_0 src1_sel:DWORD
	v_max_u32_sdwa v155, v199, v182 dst_sel:DWORD dst_unused:UNUSED_PAD src0_sel:BYTE_1 src1_sel:DWORD
	v_max_u32_sdwa v156, v199, v182 dst_sel:DWORD dst_unused:UNUSED_PAD src0_sel:BYTE_2 src1_sel:DWORD
	v_max_u32_sdwa v157, v199, v182 dst_sel:DWORD dst_unused:UNUSED_PAD src0_sel:BYTE_3 src1_sel:DWORD
	v_cvt_f32_ubyte0_e32 v154, v154
	v_cvt_f32_ubyte0_e32 v155, v155
	v_cvt_f32_ubyte0_e32 v156, v156
	v_cvt_f32_ubyte0_e32 v157, v157
	v_rcp_iflag_f32_e32 v154, v154
	v_rcp_iflag_f32_e32 v155, v155
	v_rcp_iflag_f32_e32 v156, v156
	v_rcp_iflag_f32_e32 v157, v157
	v_cvt_f32_ubyte0_e32 v178, v198
	v_cvt_f32_ubyte1_e32 v179, v198
	v_cvt_f32_ubyte2_e32 v180, v198
	v_cvt_f32_ubyte3_e32 v181, v198
	v_pk_mul_f32 v[154:155], v[154:155], v[178:179]
	v_pk_mul_f32 v[156:157], v[156:157], v[180:181]
	v_pk_mul_f32 v[4:5], v[4:5], v[154:155]
	v_pk_mul_f32 v[6:7], v[6:7], v[156:157]
	s_waitcnt vmcnt(0)
	v_max_u32_sdwa v154, v201, v182 dst_sel:DWORD dst_unused:UNUSED_PAD src0_sel:BYTE_0 src1_sel:DWORD
	v_max_u32_sdwa v155, v201, v182 dst_sel:DWORD dst_unused:UNUSED_PAD src0_sel:BYTE_1 src1_sel:DWORD
	v_max_u32_sdwa v156, v201, v182 dst_sel:DWORD dst_unused:UNUSED_PAD src0_sel:BYTE_2 src1_sel:DWORD
	v_max_u32_sdwa v157, v201, v182 dst_sel:DWORD dst_unused:UNUSED_PAD src0_sel:BYTE_3 src1_sel:DWORD
	v_cvt_f32_ubyte0_e32 v154, v154
	v_cvt_f32_ubyte0_e32 v155, v155
	v_cvt_f32_ubyte0_e32 v156, v156
	v_cvt_f32_ubyte0_e32 v157, v157
	v_rcp_iflag_f32_e32 v154, v154
	v_rcp_iflag_f32_e32 v155, v155
	v_rcp_iflag_f32_e32 v156, v156
	v_rcp_iflag_f32_e32 v157, v157
	v_cvt_f32_ubyte0_e32 v178, v200
	v_cvt_f32_ubyte1_e32 v179, v200
	v_cvt_f32_ubyte2_e32 v180, v200
	v_cvt_f32_ubyte3_e32 v181, v200
	v_pk_mul_f32 v[154:155], v[154:155], v[178:179]
	v_pk_mul_f32 v[156:157], v[156:157], v[180:181]
	v_pk_mul_f32 v[0:1], v[0:1], v[154:155]
	v_pk_mul_f32 v[2:3], v[2:3], v[156:157]
	s_branch .LBB0_2735

; #define PG8_STAGE(bufoff, gbase, voff) do { _Pragma("unroll") for (int _i = 0; _i < 2; ++_i) \
;         __builtin_amdgcn_global_load_lds((const unsigned*)((const char*)(gbase) + (voff)[_i]), (PG8_LAS unsigned*)(lds + (bufoff) + ldsw + _i * 8192), 16, 0, 0); } while (0)
; #define PG8_LDA(dst, b, h) do { _Pragma("unroll") for (int m = 0; m < 4; ++m) _Pragma("unroll") for (int k = 0; k < 2; ++k) dst[m][k] = *(const PG8_LAS bf16x8*)(lds + PG8_SA(b, h) + aoff + m * 2048 + k * 1024); } while (0)
; #define PG8_LDB(dst, b, h) do { _Pragma("unroll") for (int n = 0; n < 2; ++n) _Pragma("unroll") for (int k = 0; k < 2; ++k) dst[n][k] = *(const PG8_LAS bf16x8*)(lds + PG8_SB(b, h) + boff + n * 2048 + k * 1024); } while (0)
; #define PG8_MMA(ai, bj, At, Bt) do { __builtin_amdgcn_s_setprio(1); _Pragma("unroll") for (int m = 0; m < 4; ++m) _Pragma("unroll") for (int n = 0; n < 2; ++n) _Pragma("unroll") for (int k = 0; k < 2; ++k) \
;         acc[ai][bj][m][n] = __builtin_amdgcn_mfma_f32_16x16x32_bf16(Bt[n][k], At[m][k], acc[ai][bj][m][n], 0, 0, 0); __builtin_amdgcn_s_setprio(0); } while (0)
; #define PG8_WAIT_V(n) asm volatile("s_waitcnt vmcnt(" #n ")" ::: "memory")
; #define PG8_WAIT_L(n) asm volatile("s_waitcnt lgkmcnt(" #n ")" ::: "memory")
; #define PG8_BAR __builtin_amdgcn_s_barrier()
; #define PG8_SCHED __builtin_amdgcn_sched_barrier(0)
; template <class Epi, class Sched>
; __device__ __forceinline__ void gemm_phase(PG8_LAS unsigned char* lds, const Gemm g, const Sched& S, const Epi& E) {
;     ...
;             PG8_LDB(B0, 0, 0); PG8_SCHED; PG8_LDA(At, 0, 0); PG8_STAGE(PG8_SA(1, 1), a1 + hstep, voffA);
;             PG8_WAIT_L(8); PG8_BAR; PG8_WAIT_L(0); PG8_MMA(0, 0, At, B0); PG8_BAR; PG8_SCHED;
;             PG8_LDB(B1, 0, 1); PG8_STAGE(PG8_SB(0, 0), b2, voffB);
;             PG8_BAR; PG8_WAIT_L(0); PG8_MMA(0, 1, At, B1); PG8_BAR;
;             PG8_LDA(At, 0, 1); PG8_STAGE(PG8_SA(0, 0), a2, voffA);
;             PG8_BAR; PG8_WAIT_L(0); PG8_MMA(1, 0, At, B0); PG8_BAR; PG8_SCHED;
;             PG8_STAGE(PG8_SB(0, 1), b2 + hstep, voffB);
;             PG8_WAIT_V(6); PG8_BAR; PG8_MMA(1, 1, At, B1); PG8_BAR;
.LBB0_2754:
	s_add_u32 s14, s12, 0xfffc0080
	s_addc_u32 s15, s13, -1
	s_add_i32 s37, 0, 0x10000
	v_add_u32_e32 v140, s37, v142
	ds_read_b128 v[144:147], v140
	ds_read_b128 v[148:151], v140 offset:1024
	ds_read_b128 v[162:165], v140 offset:2048
	ds_read_b128 v[166:169], v140 offset:3072
	s_cmp_eq_u32 s36, 12
	s_cselect_b32 s17, s5, s15
	s_cselect_b32 s16, s31, s14
	s_cselect_b32 s15, s3, s35
	s_cselect_b32 s14, s33, s34
	v_lshl_add_u64 v[140:141], s[12:13], 0, v[136:137]
	s_add_i32 m0, s23, 0xc000
	ds_read_b128 v[170:173], v143
	ds_read_b128 v[174:177], v143 offset:1024
	ds_read_b128 v[178:181], v143 offset:2048
	ds_read_b128 v[188:191], v143 offset:3072
	ds_read_b128 v[192:195], v143 offset:4096
	ds_read_b128 v[196:199], v143 offset:5120
	ds_read_b128 v[200:203], v143 offset:6144
	ds_read_b128 v[204:207], v143 offset:7168
	global_load_lds_dwordx4 v[140:141], off
	v_lshl_add_u64 v[140:141], s[12:13], 0, v[138:139]
	s_add_i32 m0, s23, 0xe000
	s_nop 0
	global_load_lds_dwordx4 v[140:141], off
	s_waitcnt lgkmcnt(8)
	s_barrier
	s_waitcnt lgkmcnt(0)
	s_setprio 1
	s_waitcnt lgkmcnt(0)
	v_mfma_f32_16x16x32_bf16 v[130:133], v[144:147], v[170:173], v[130:133]
	v_mfma_f32_16x16x32_bf16 v[126:129], v[162:165], v[170:173], v[126:129]
	v_mfma_f32_16x16x32_bf16 v[114:117], v[144:147], v[178:181], v[114:117]
	v_mfma_f32_16x16x32_bf16 v[110:113], v[162:165], v[178:181], v[110:113]
	v_mfma_f32_16x16x32_bf16 v[98:101], v[144:147], v[192:195], v[98:101]
	v_mfma_f32_16x16x32_bf16 v[94:97], v[162:165], v[192:195], v[94:97]
	v_mfma_f32_16x16x32_bf16 v[82:85], v[144:147], v[200:203], v[82:85]
	v_mfma_f32_16x16x32_bf16 v[78:81], v[162:165], v[200:203], v[78:81]
	v_mfma_f32_16x16x32_bf16 v[130:133], v[148:151], v[174:177], v[130:133]
	v_mfma_f32_16x16x32_bf16 v[126:129], v[166:169], v[174:177], v[126:129]
	v_mfma_f32_16x16x32_bf16 v[114:117], v[148:151], v[188:191], v[114:117]
	v_mfma_f32_16x16x32_bf16 v[110:113], v[166:169], v[188:191], v[110:113]
	v_mfma_f32_16x16x32_bf16 v[98:101], v[148:151], v[196:199], v[98:101]
	v_mfma_f32_16x16x32_bf16 v[94:97], v[166:169], v[196:199], v[94:97]
	v_mfma_f32_16x16x32_bf16 v[82:85], v[148:151], v[204:207], v[82:85]
	v_mfma_f32_16x16x32_bf16 v[78:81], v[166:169], v[204:207], v[78:81]
	s_setprio 0
	s_barrier
	s_add_i32 s40, 0, 0x14000
	v_add_u32_e32 v140, s40, v142
	s_add_i32 s37, s37, s21
	ds_read_b128 v[208:211], v140
	ds_read_b128 v[212:215], v140 offset:1024
	ds_read_b128 v[216:219], v140 offset:2048
	ds_read_b128 v[220:223], v140 offset:3072
	v_lshl_add_u64 v[140:141], s[14:15], 0, v[134:135]
	s_mov_b32 m0, s37
	v_lshl_add_u64 v[154:155], s[14:15], 0, v[18:19]
	global_load_lds_dwordx4 v[140:141], off
	s_add_i32 m0, s37, 0x2000
	s_nop 0
	global_load_lds_dwordx4 v[154:155], off
	s_barrier
	s_waitcnt lgkmcnt(0)
	s_setprio 1
	s_waitcnt lgkmcnt(0)
	v_mfma_f32_16x16x32_bf16 v[122:125], v[208:211], v[170:173], v[122:125]
	v_mfma_f32_16x16x32_bf16 v[118:121], v[216:219], v[170:173], v[118:121]
	v_mfma_f32_16x16x32_bf16 v[106:109], v[208:211], v[178:181], v[106:109]
	v_mfma_f32_16x16x32_bf16 v[102:105], v[216:219], v[178:181], v[102:105]
	v_mfma_f32_16x16x32_bf16 v[90:93], v[208:211], v[192:195], v[90:93]
	v_mfma_f32_16x16x32_bf16 v[86:89], v[216:219], v[192:195], v[86:89]
	v_mfma_f32_16x16x32_bf16 v[74:77], v[208:211], v[200:203], v[74:77]
	v_mfma_f32_16x16x32_bf16 v[70:73], v[216:219], v[200:203], v[70:73]
	v_mfma_f32_16x16x32_bf16 v[122:125], v[212:215], v[174:177], v[122:125]
	v_mfma_f32_16x16x32_bf16 v[118:121], v[220:223], v[174:177], v[118:121]
	v_mfma_f32_16x16x32_bf16 v[106:109], v[212:215], v[188:191], v[106:109]
	v_mfma_f32_16x16x32_bf16 v[102:105], v[220:223], v[188:191], v[102:105]
	v_mfma_f32_16x16x32_bf16 v[90:93], v[212:215], v[196:199], v[90:93]
	v_mfma_f32_16x16x32_bf16 v[86:89], v[220:223], v[196:199], v[86:89]
	v_mfma_f32_16x16x32_bf16 v[74:77], v[212:215], v[204:207], v[74:77]
	v_mfma_f32_16x16x32_bf16 v[70:73], v[220:223], v[204:207], v[70:73]
	s_setprio 0
	s_mov_b32 m0, s23
	v_lshl_add_u64 v[156:157], s[16:17], 0, v[134:135]
	s_barrier
	ds_read_b128 v[170:173], v143 offset:16384
	ds_read_b128 v[174:177], v143 offset:17408
	ds_read_b128 v[178:181], v143 offset:18432
	ds_read_b128 v[188:191], v143 offset:19456
	ds_read_b128 v[192:195], v143 offset:20480
	ds_read_b128 v[196:199], v143 offset:21504
	ds_read_b128 v[200:203], v143 offset:22528
	ds_read_b128 v[204:207], v143 offset:23552
	global_load_lds_dwordx4 v[156:157], off
	v_lshl_add_u64 v[186:187], s[16:17], 0, v[18:19]
	s_mov_b32 m0, s24
	s_nop 0
	global_load_lds_dwordx4 v[186:187], off
	s_barrier
	s_waitcnt lgkmcnt(0)
	s_setprio 1
	s_waitcnt lgkmcnt(0)
	v_mfma_f32_16x16x32_bf16 v[66:69], v[144:147], v[170:173], v[66:69]
	v_mfma_f32_16x16x32_bf16 v[62:65], v[162:165], v[170:173], v[62:65]
	v_mfma_f32_16x16x32_bf16 v[50:53], v[144:147], v[178:181], v[50:53]
	v_mfma_f32_16x16x32_bf16 v[46:49], v[162:165], v[178:181], v[46:49]
	v_mfma_f32_16x16x32_bf16 v[34:37], v[144:147], v[192:195], v[34:37]
	v_mfma_f32_16x16x32_bf16 v[30:33], v[162:165], v[192:195], v[30:33]
	v_mfma_f32_16x16x32_bf16 v[12:15], v[144:147], v[200:203], v[12:15]
	v_mfma_f32_16x16x32_bf16 v[8:11], v[162:165], v[200:203], v[8:11]
	v_mfma_f32_16x16x32_bf16 v[66:69], v[148:151], v[174:177], v[66:69]
	v_mfma_f32_16x16x32_bf16 v[62:65], v[166:169], v[174:177], v[62:65]
	v_mfma_f32_16x16x32_bf16 v[50:53], v[148:151], v[188:191], v[50:53]
	v_mfma_f32_16x16x32_bf16 v[46:49], v[166:169], v[188:191], v[46:49]
	v_mfma_f32_16x16x32_bf16 v[34:37], v[148:151], v[196:199], v[34:37]
	v_mfma_f32_16x16x32_bf16 v[30:33], v[166:169], v[196:199], v[30:33]
	v_mfma_f32_16x16x32_bf16 v[12:15], v[148:151], v[204:207], v[12:15]
	v_mfma_f32_16x16x32_bf16 v[8:11], v[166:169], v[204:207], v[8:11]
	s_setprio 0
	s_barrier
; #define PG8_STAGE(bufoff, gbase, voff) do { _Pragma("unroll") for (int _i = 0; _i < 2; ++_i) \
;         __builtin_amdgcn_global_load_lds((const unsigned*)((const char*)(gbase) + (voff)[_i]), (PG8_LAS unsigned*)(lds + (bufoff) + ldsw + _i * 8192), 16, 0, 0); } while (0)
; #define PG8_LDA(dst, b, h) do { _Pragma("unroll") for (int m = 0; m < 4; ++m) _Pragma("unroll") for (int k = 0; k < 2; ++k) dst[m][k] = *(const PG8_LAS bf16x8*)(lds + PG8_SA(b, h) + aoff + m * 2048 + k * 1024); } while (0)
; #define PG8_LDB(dst, b, h) do { _Pragma("unroll") for (int n = 0; n < 2; ++n) _Pragma("unroll") for (int k = 0; k < 2; ++k) dst[n][k] = *(const PG8_LAS bf16x8*)(lds + PG8_SB(b, h) + boff + n * 2048 + k * 1024); } while (0)
; #define PG8_MMA(ai, bj, At, Bt) do { __builtin_amdgcn_s_setprio(1); _Pragma("unroll") for (int m = 0; m < 4; ++m) _Pragma("unroll") for (int n = 0; n < 2; ++n) _Pragma("unroll") for (int k = 0; k < 2; ++k) \
;         acc[ai][bj][m][n] = __builtin_amdgcn_mfma_f32_16x16x32_bf16(Bt[n][k], At[m][k], acc[ai][bj][m][n], 0, 0, 0); __builtin_amdgcn_s_setprio(0); } while (0)
; #define PG8_WAIT_V(n) asm volatile("s_waitcnt vmcnt(" #n ")" ::: "memory")
; #define PG8_WAIT_L(n) asm volatile("s_waitcnt lgkmcnt(" #n ")" ::: "memory")
; #define PG8_BAR __builtin_amdgcn_s_barrier()
; #define PG8_SCHED __builtin_amdgcn_sched_barrier(0)
; template <class Epi, class Sched>
; __device__ __forceinline__ void gemm_phase(PG8_LAS unsigned char* lds, const Gemm g, const Sched& S, const Epi& E) {
;     ...
;             PG8_WAIT_V(6); PG8_BAR; PG8_MMA(1, 1, At, B1); PG8_BAR;
;             PG8_LDB(B0, 1, 0); PG8_SCHED; PG8_LDA(At, 1, 0); PG8_STAGE(PG8_SA(0, 1), a2 + hstep, voffA);
;             PG8_WAIT_L(8); PG8_BAR; PG8_WAIT_L(0); PG8_MMA(0, 0, At, B0); PG8_BAR; PG8_SCHED;
;             PG8_LDB(B1, 1, 1); PG8_STAGE(PG8_SB(1, 0), b3, voffB);
;             PG8_BAR; PG8_WAIT_L(0); PG8_MMA(0, 1, At, B1); PG8_BAR;
;             PG8_LDA(At, 1, 1); PG8_STAGE(PG8_SA(1, 0), a3, voffA);
;             PG8_BAR; PG8_WAIT_L(0); PG8_MMA(1, 0, At, B0); PG8_BAR; PG8_SCHED;
	s_add_u32 s38, s14, 0x40000
	s_addc_u32 s39, s15, 0
	s_add_i32 s37, s40, s21
	v_lshl_add_u64 v[144:145], s[38:39], 0, v[134:135]
	s_mov_b32 m0, s37
	s_nop 0
	global_load_lds_dwordx4 v[144:145], off
	v_lshl_add_u64 v[144:145], s[38:39], 0, v[18:19]
	s_add_i32 m0, s37, 0x2000
	s_nop 0
	global_load_lds_dwordx4 v[144:145], off
	s_waitcnt vmcnt(6)
	s_barrier
	s_setprio 1
	v_mfma_f32_16x16x32_bf16 v[58:61], v[208:211], v[170:173], v[58:61]
	v_mfma_f32_16x16x32_bf16 v[54:57], v[216:219], v[170:173], v[54:57]
	v_mfma_f32_16x16x32_bf16 v[42:45], v[208:211], v[178:181], v[42:45]
	v_mfma_f32_16x16x32_bf16 v[38:41], v[216:219], v[178:181], v[38:41]
	v_mfma_f32_16x16x32_bf16 v[26:29], v[208:211], v[192:195], v[26:29]
	v_mfma_f32_16x16x32_bf16 v[22:25], v[216:219], v[192:195], v[22:25]
	v_mfma_f32_16x16x32_bf16 v[4:7], v[208:211], v[200:203], v[4:7]
	v_mfma_f32_16x16x32_bf16 v[0:3], v[216:219], v[200:203], v[0:3]
	v_mfma_f32_16x16x32_bf16 v[58:61], v[212:215], v[174:177], v[58:61]
	v_mfma_f32_16x16x32_bf16 v[54:57], v[220:223], v[174:177], v[54:57]
	v_mfma_f32_16x16x32_bf16 v[42:45], v[212:215], v[188:191], v[42:45]
	v_mfma_f32_16x16x32_bf16 v[38:41], v[220:223], v[188:191], v[38:41]
	v_mfma_f32_16x16x32_bf16 v[26:29], v[212:215], v[196:199], v[26:29]
	v_mfma_f32_16x16x32_bf16 v[22:25], v[220:223], v[196:199], v[22:25]
	v_mfma_f32_16x16x32_bf16 v[4:7], v[212:215], v[204:207], v[4:7]
	v_mfma_f32_16x16x32_bf16 v[0:3], v[220:223], v[204:207], v[0:3]
	s_setprio 0
	s_add_i32 s37, 0, 0x18000
	v_add_u32_e32 v166, s37, v142
	s_barrier
	ds_read_b128 v[144:147], v166
	ds_read_b128 v[148:151], v166 offset:1024
	ds_read_b128 v[162:165], v166 offset:2048
	ds_read_b128 v[166:169], v166 offset:3072
	s_add_u32 s16, s16, 0x40000
	s_addc_u32 s17, s17, 0
	s_mov_b32 m0, s25
	v_lshl_add_u64 v[208:209], s[16:17], 0, v[134:135]
	ds_read_b128 v[170:173], v143 offset:32768
	ds_read_b128 v[174:177], v143 offset:33792
	ds_read_b128 v[178:181], v143 offset:34816
	ds_read_b128 v[188:191], v143 offset:35840
	ds_read_b128 v[192:195], v143 offset:36864
	ds_read_b128 v[196:199], v143 offset:37888
	ds_read_b128 v[200:203], v143 offset:38912
	ds_read_b128 v[204:207], v143 offset:39936
	global_load_lds_dwordx4 v[208:209], off
	v_lshl_add_u64 v[208:209], s[16:17], 0, v[18:19]
	s_mov_b32 m0, s26
	s_nop 0
	global_load_lds_dwordx4 v[208:209], off
	s_waitcnt lgkmcnt(8)
	s_barrier
	s_waitcnt lgkmcnt(0)
	s_setprio 1
	s_waitcnt lgkmcnt(0)
	v_mfma_f32_16x16x32_bf16 v[130:133], v[144:147], v[170:173], v[130:133]
	v_mfma_f32_16x16x32_bf16 v[126:129], v[162:165], v[170:173], v[126:129]
	v_mfma_f32_16x16x32_bf16 v[114:117], v[144:147], v[178:181], v[114:117]
	v_mfma_f32_16x16x32_bf16 v[110:113], v[162:165], v[178:181], v[110:113]
	v_mfma_f32_16x16x32_bf16 v[98:101], v[144:147], v[192:195], v[98:101]
	v_mfma_f32_16x16x32_bf16 v[94:97], v[162:165], v[192:195], v[94:97]
	v_mfma_f32_16x16x32_bf16 v[82:85], v[144:147], v[200:203], v[82:85]
	v_mfma_f32_16x16x32_bf16 v[78:81], v[162:165], v[200:203], v[78:81]
	v_mfma_f32_16x16x32_bf16 v[130:133], v[148:151], v[174:177], v[130:133]
	v_mfma_f32_16x16x32_bf16 v[126:129], v[166:169], v[174:177], v[126:129]
	v_mfma_f32_16x16x32_bf16 v[114:117], v[148:151], v[188:191], v[114:117]
	v_mfma_f32_16x16x32_bf16 v[110:113], v[166:169], v[188:191], v[110:113]
	v_mfma_f32_16x16x32_bf16 v[98:101], v[148:151], v[196:199], v[98:101]
	v_mfma_f32_16x16x32_bf16 v[94:97], v[166:169], v[196:199], v[94:97]
	v_mfma_f32_16x16x32_bf16 v[82:85], v[148:151], v[204:207], v[82:85]
	v_mfma_f32_16x16x32_bf16 v[78:81], v[166:169], v[204:207], v[78:81]
	s_setprio 0
	s_barrier
	s_add_i32 s16, 0, 0x1c000
	s_add_i32 s17, s37, s21
	v_add_u32_e32 v220, s16, v142
	v_lshl_add_u64 v[140:141], v[140:141], 0, s[42:43]
	s_mov_b32 m0, s17
	ds_read_b128 v[208:211], v220
	ds_read_b128 v[212:215], v220 offset:1024
	ds_read_b128 v[216:219], v220 offset:2048
	ds_read_b128 v[220:223], v220 offset:3072
	global_load_lds_dwordx4 v[140:141], off
	v_lshl_add_u64 v[140:141], v[154:155], 0, s[42:43]
	s_add_i32 m0, s17, 0x2000
	s_nop 0
	global_load_lds_dwordx4 v[140:141], off
	s_barrier
	s_waitcnt lgkmcnt(0)
	s_setprio 1
	s_waitcnt lgkmcnt(0)
	v_mfma_f32_16x16x32_bf16 v[122:125], v[208:211], v[170:173], v[122:125]
	v_mfma_f32_16x16x32_bf16 v[118:121], v[216:219], v[170:173], v[118:121]
	v_mfma_f32_16x16x32_bf16 v[106:109], v[208:211], v[178:181], v[106:109]
	v_mfma_f32_16x16x32_bf16 v[102:105], v[216:219], v[178:181], v[102:105]
	v_mfma_f32_16x16x32_bf16 v[90:93], v[208:211], v[192:195], v[90:93]
	v_mfma_f32_16x16x32_bf16 v[86:89], v[216:219], v[192:195], v[86:89]
	v_mfma_f32_16x16x32_bf16 v[74:77], v[208:211], v[200:203], v[74:77]
	v_mfma_f32_16x16x32_bf16 v[70:73], v[216:219], v[200:203], v[70:73]
	v_mfma_f32_16x16x32_bf16 v[122:125], v[212:215], v[174:177], v[122:125]
	v_mfma_f32_16x16x32_bf16 v[118:121], v[220:223], v[174:177], v[118:121]
	v_mfma_f32_16x16x32_bf16 v[106:109], v[212:215], v[188:191], v[106:109]
	v_mfma_f32_16x16x32_bf16 v[102:105], v[220:223], v[188:191], v[102:105]
	v_mfma_f32_16x16x32_bf16 v[90:93], v[212:215], v[196:199], v[90:93]
	v_mfma_f32_16x16x32_bf16 v[86:89], v[220:223], v[196:199], v[86:89]
	v_mfma_f32_16x16x32_bf16 v[74:77], v[212:215], v[204:207], v[74:77]
	v_mfma_f32_16x16x32_bf16 v[70:73], v[220:223], v[204:207], v[70:73]
	s_setprio 0
	s_mov_b32 m0, s27
	v_lshl_add_u64 v[140:141], v[156:157], 0, s[42:43]
	s_barrier
	ds_read_b128 v[170:173], v143 offset:49152
	ds_read_b128 v[174:177], v143 offset:50176
	ds_read_b128 v[178:181], v143 offset:51200
	ds_read_b128 v[188:191], v143 offset:52224
	ds_read_b128 v[192:195], v143 offset:53248
	ds_read_b128 v[196:199], v143 offset:54272
	ds_read_b128 v[200:203], v143 offset:55296
	ds_read_b128 v[204:207], v143 offset:56320
	global_load_lds_dwordx4 v[140:141], off
	v_lshl_add_u64 v[140:141], v[186:187], 0, s[42:43]
	s_mov_b32 m0, s28
	s_nop 0
	global_load_lds_dwordx4 v[140:141], off
	s_barrier
; DI bf16x4 pack4(float a, float b, float c, float d) { u32x2v u; u.x = pk2(a, b); u.y = pk2(c, d); return __builtin_bit_cast(bf16x4, u); }
; #define PG8_STAGE(bufoff, gbase, voff) do { _Pragma("unroll") for (int _i = 0; _i < 2; ++_i) \
;         __builtin_amdgcn_global_load_lds((const unsigned*)((const char*)(gbase) + (voff)[_i]), (PG8_LAS unsigned*)(lds + (bufoff) + ldsw + _i * 8192), 16, 0, 0); } while (0)
; #define PG8_MMA(ai, bj, At, Bt) do { __builtin_amdgcn_s_setprio(1); _Pragma("unroll") for (int m = 0; m < 4; ++m) _Pragma("unroll") for (int n = 0; n < 2; ++n) _Pragma("unroll") for (int k = 0; k < 2; ++k) \
;         acc[ai][bj][m][n] = __builtin_amdgcn_mfma_f32_16x16x32_bf16(Bt[n][k], At[m][k], acc[ai][bj][m][n], 0, 0, 0); __builtin_amdgcn_s_setprio(0); } while (0)
; #define PG8_WAIT_V(n) asm volatile("s_waitcnt vmcnt(" #n ")" ::: "memory")
; template <class Epi, class Sched>
; __device__ __forceinline__ void gemm_phase(PG8_LAS unsigned char* lds, const Gemm g, const Sched& S, const Epi& E) {
;     ...
;             PG8_BAR; PG8_WAIT_L(0); PG8_MMA(1, 0, At, B0); PG8_BAR; PG8_SCHED;
;             PG8_STAGE(PG8_SB(1, 1), b3 + hstep, voffB);
;             PG8_WAIT_V(6); PG8_BAR; PG8_MMA(1, 1, At, B1); PG8_BAR;
;   DI void operator()(const f32x4 (&acc)[2][2][4][2], const pg8::Unit& u, int wr, int wc, int fr, int fq) const {
;     ...
;     for (int ai = 0; ai < 2; ++ai)
; #pragma unroll
;       for (int m = 0; m < 4; ++m) {
;         const int row = u.pm * 256 + 128 * ai + 64 * wr + 16 * m + fr;
; #pragma unroll
;         for (int bj = 0; bj < 2; ++bj)
; #pragma unroll
;           for (int n = 0; n < 2; ++n) {
;             const size_t idx = (size_t)row * 1024 + u.pn * 256 + 128 * bj + 32 * wc + 16 * n + 4 * fq;
;             const f32x4 a = acc[ai][bj][m][n];
;             if (MODE == 0) {
;               const unsigned g = *reinterpret_cast<const unsigned*>(reinterpret_cast<const unsigned char*>(p.ws + OFF_RB) + idx);
;               const float k = 1.f / 255.f;
;               st4(MERGED + idx, pack4((float)(g & 255u) * k * a[0], (float)((g >> 8) & 255u) * k * a[1], (float)((g >> 16) & 255u) * k * a[2], (float)(g >> 24) * k * a[3]));
;             } else {
;               f32x4 x = *reinterpret_cast<const f32x4*>(p.out + idx);
;               x = x * ALPHA + a;
;               *reinterpret_cast<f32x4*>(p.out + idx) = x;
;             }
	s_waitcnt lgkmcnt(0)
	s_setprio 1
	s_waitcnt lgkmcnt(0)
	v_mfma_f32_16x16x32_bf16 v[66:69], v[144:147], v[170:173], v[66:69]
	v_mfma_f32_16x16x32_bf16 v[62:65], v[162:165], v[170:173], v[62:65]
	v_mfma_f32_16x16x32_bf16 v[50:53], v[144:147], v[178:181], v[50:53]
	v_mfma_f32_16x16x32_bf16 v[46:49], v[162:165], v[178:181], v[46:49]
	v_mfma_f32_16x16x32_bf16 v[34:37], v[144:147], v[192:195], v[34:37]
	v_mfma_f32_16x16x32_bf16 v[30:33], v[162:165], v[192:195], v[30:33]
	v_mfma_f32_16x16x32_bf16 v[12:15], v[144:147], v[200:203], v[12:15]
	v_mfma_f32_16x16x32_bf16 v[8:11], v[162:165], v[200:203], v[8:11]
	v_mfma_f32_16x16x32_bf16 v[66:69], v[148:151], v[174:177], v[66:69]
	v_mfma_f32_16x16x32_bf16 v[62:65], v[166:169], v[174:177], v[62:65]
	v_mfma_f32_16x16x32_bf16 v[50:53], v[148:151], v[188:191], v[50:53]
	v_mfma_f32_16x16x32_bf16 v[46:49], v[166:169], v[188:191], v[46:49]
	v_mfma_f32_16x16x32_bf16 v[34:37], v[148:151], v[196:199], v[34:37]
	v_mfma_f32_16x16x32_bf16 v[30:33], v[166:169], v[196:199], v[30:33]
	v_mfma_f32_16x16x32_bf16 v[12:15], v[148:151], v[204:207], v[12:15]
	v_mfma_f32_16x16x32_bf16 v[8:11], v[166:169], v[204:207], v[8:11]
	s_setprio 0
	s_barrier
	s_add_u32 s14, s14, 0x40080
	s_addc_u32 s15, s15, 0
	s_add_i32 s16, s16, s21
	v_lshl_add_u64 v[140:141], s[14:15], 0, v[134:135]
	s_mov_b32 m0, s16
	s_nop 0
	global_load_lds_dwordx4 v[140:141], off
	v_lshl_add_u64 v[140:141], s[14:15], 0, v[18:19]
	s_add_i32 m0, s16, 0x2000
	s_nop 0
	global_load_lds_dwordx4 v[140:141], off
	s_waitcnt vmcnt(6)
	s_barrier
	s_setprio 1
	v_mfma_f32_16x16x32_bf16 v[58:61], v[208:211], v[170:173], v[58:61]
	v_mfma_f32_16x16x32_bf16 v[54:57], v[216:219], v[170:173], v[54:57]
	v_mfma_f32_16x16x32_bf16 v[42:45], v[208:211], v[178:181], v[42:45]
	v_mfma_f32_16x16x32_bf16 v[38:41], v[216:219], v[178:181], v[38:41]
	v_mfma_f32_16x16x32_bf16 v[26:29], v[208:211], v[192:195], v[26:29]
	v_mfma_f32_16x16x32_bf16 v[22:25], v[216:219], v[192:195], v[22:25]
	v_mfma_f32_16x16x32_bf16 v[4:7], v[208:211], v[200:203], v[4:7]
	v_mfma_f32_16x16x32_bf16 v[0:3], v[216:219], v[200:203], v[0:3]
	v_mfma_f32_16x16x32_bf16 v[58:61], v[212:215], v[174:177], v[58:61]
	v_mfma_f32_16x16x32_bf16 v[54:57], v[220:223], v[174:177], v[54:57]
	v_mfma_f32_16x16x32_bf16 v[42:45], v[212:215], v[188:191], v[42:45]
	v_mfma_f32_16x16x32_bf16 v[38:41], v[220:223], v[188:191], v[38:41]
	v_mfma_f32_16x16x32_bf16 v[26:29], v[212:215], v[196:199], v[26:29]
	v_mfma_f32_16x16x32_bf16 v[22:25], v[220:223], v[196:199], v[22:25]
	v_mfma_f32_16x16x32_bf16 v[4:7], v[212:215], v[204:207], v[4:7]
	v_mfma_f32_16x16x32_bf16 v[0:3], v[220:223], v[204:207], v[0:3]
	s_setprio 0
	s_add_i32 s36, s36, 2
	s_add_u32 s12, s12, 0x100
	s_addc_u32 s13, s13, 0
	s_add_u32 s34, s34, 0x100
	s_addc_u32 s35, s35, 0
	s_cmp_gt_u32 s36, 13
	s_barrier
	s_cbranch_scc0 .LBB0_2754
	v_lshl_add_u32 v140, s10, 8, v21
	s_lshl_b32 s10, s11, 8
	v_ashrrev_i32_e32 v141, 31, v140
	s_ashr_i32 s11, s10, 31
	v_lshlrev_b64 v[144:145], 12, v[140:141]
	v_readlane_b32 s14, v249, 4
	v_readlane_b32 s15, v249, 5
	s_lshl_b64 s[10:11], s[10:11], 2
	v_readlane_b32 s12, v251, 6
	v_readlane_b32 s13, v251, 7
	s_mov_b32 s16, 0x3fd744fd
	s_nop 1
	v_lshl_add_u64 v[144:145], s[14:15], 0, v[144:145]
	v_lshl_add_u64 v[144:145], v[144:145], 0, s[10:11]
	v_lshl_add_u64 v[144:145], v[144:145], 0, s[12:13]
	v_lshl_add_u64 v[148:149], v[144:145], 0, v[16:17]
	s_mov_b64 s[12:13], 0x10000
	v_lshl_add_u64 v[150:151], v[148:149], 0, s[12:13]
	s_mov_b64 s[14:15], 0x20000
	v_lshl_add_u64 v[154:155], v[148:149], 0, s[14:15]
	s_mov_b64 s[12:13], 0x30000
	v_lshl_add_u64 v[156:157], v[148:149], 0, s[12:13]
	s_mov_b64 s[14:15], 0x80000
	v_lshl_add_u64 v[162:163], v[148:149], 0, s[14:15]
	s_mov_b64 s[12:13], 0x90000
	v_lshl_add_u64 v[164:165], v[148:149], 0, s[12:13]
	s_mov_b64 s[14:15], 0xa0000
	v_lshl_add_u64 v[166:167], v[148:149], 0, s[14:15]
	s_mov_b64 s[12:13], 0xb0000
	v_lshl_add_u64 v[168:169], v[148:149], 0, s[12:13]
	global_load_dwordx4 v[170:173], v[148:149], off
	global_load_dwordx4 v[174:177], v[148:149], off offset:64
	global_load_dwordx4 v[178:181], v[148:149], off offset:512
	global_load_dwordx4 v[186:189], v[148:149], off offset:576
	global_load_dwordx4 v[190:193], v[150:151], off
	global_load_dwordx4 v[194:197], v[150:151], off offset:64
	global_load_dwordx4 v[198:201], v[150:151], off offset:512
	global_load_dwordx4 v[204:207], v[150:151], off offset:576
	global_load_dwordx4 v[208:211], v[154:155], off
	global_load_dwordx4 v[212:215], v[154:155], off offset:64
	global_load_dwordx4 v[216:219], v[154:155], off offset:512
	global_load_dwordx4 v[220:223], v[154:155], off offset:576
	global_load_dwordx4 v[224:227], v[156:157], off
	global_load_dwordx4 v[228:231], v[156:157], off offset:64
	global_load_dwordx4 v[232:235], v[156:157], off offset:512
	global_load_dwordx4 v[236:239], v[156:157], off offset:576
	s_waitcnt vmcnt(15)
	v_pk_fma_f32 v[132:133], v[172:173], s[16:17], v[132:133] op_sel_hi:[1,0,1]
	v_pk_fma_f32 v[130:131], v[170:171], s[16:17], v[130:131] op_sel_hi:[1,0,1]
	global_store_dwordx4 v[148:149], v[130:133], off
	global_load_dwordx4 v[170:173], v[162:163], off
	s_waitcnt vmcnt(16)
	v_pk_fma_f32 v[128:129], v[176:177], s[16:17], v[128:129] op_sel_hi:[1,0,1]
	v_pk_fma_f32 v[126:127], v[174:175], s[16:17], v[126:127] op_sel_hi:[1,0,1]
	global_store_dwordx4 v[148:149], v[126:129], off offset:64
	global_load_dwordx4 v[174:177], v[162:163], off offset:64
	s_waitcnt vmcnt(17)
	v_pk_fma_f32 v[124:125], v[180:181], s[16:17], v[124:125] op_sel_hi:[1,0,1]
	v_pk_fma_f32 v[122:123], v[178:179], s[16:17], v[122:123] op_sel_hi:[1,0,1]
	global_store_dwordx4 v[148:149], v[122:125], off offset:512
	global_load_dwordx4 v[178:181], v[162:163], off offset:512
	s_waitcnt vmcnt(18)
; DI bf16x4 pack4(float a, float b, float c, float d) { u32x2v u; u.x = pk2(a, b); u.y = pk2(c, d); return __builtin_bit_cast(bf16x4, u); }
;   DI void operator()(const f32x4 (&acc)[2][2][4][2], const pg8::Unit& u, int wr, int wc, int fr, int fq) const {
;     ...
;     for (int ai = 0; ai < 2; ++ai)
; #pragma unroll
;       for (int m = 0; m < 4; ++m) {
;         const int row = u.pm * 256 + 128 * ai + 64 * wr + 16 * m + fr;
; #pragma unroll
;         for (int bj = 0; bj < 2; ++bj)
; #pragma unroll
;           for (int n = 0; n < 2; ++n) {
;             const size_t idx = (size_t)row * 1024 + u.pn * 256 + 128 * bj + 32 * wc + 16 * n + 4 * fq;
;             const f32x4 a = acc[ai][bj][m][n];
;             if (MODE == 0) {
;               const unsigned g = *reinterpret_cast<const unsigned*>(reinterpret_cast<const unsigned char*>(p.ws + OFF_RB) + idx);
;               const float k = 1.f / 255.f;
;               st4(MERGED + idx, pack4((float)(g & 255u) * k * a[0], (float)((g >> 8) & 255u) * k * a[1], (float)((g >> 16) & 255u) * k * a[2], (float)(g >> 24) * k * a[3]));
;             } else {
;               f32x4 x = *reinterpret_cast<const f32x4*>(p.out + idx);
;               x = x * ALPHA + a;
;               *reinterpret_cast<f32x4*>(p.out + idx) = x;
;             }
	v_pk_fma_f32 v[120:121], v[188:189], s[16:17], v[120:121] op_sel_hi:[1,0,1]
	v_pk_fma_f32 v[118:119], v[186:187], s[16:17], v[118:119] op_sel_hi:[1,0,1]
	global_store_dwordx4 v[148:149], v[118:121], off offset:576
	global_load_dwordx4 v[186:189], v[162:163], off offset:576
	s_waitcnt vmcnt(19)
	v_pk_fma_f32 v[116:117], v[192:193], s[16:17], v[116:117] op_sel_hi:[1,0,1]
	v_pk_fma_f32 v[114:115], v[190:191], s[16:17], v[114:115] op_sel_hi:[1,0,1]
	global_store_dwordx4 v[150:151], v[114:117], off
	global_load_dwordx4 v[190:193], v[164:165], off
	s_waitcnt vmcnt(20)
	v_pk_fma_f32 v[112:113], v[196:197], s[16:17], v[112:113] op_sel_hi:[1,0,1]
	v_pk_fma_f32 v[110:111], v[194:195], s[16:17], v[110:111] op_sel_hi:[1,0,1]
	global_store_dwordx4 v[150:151], v[110:113], off offset:64
	global_load_dwordx4 v[194:197], v[164:165], off offset:64
	s_waitcnt vmcnt(21)
	v_pk_fma_f32 v[108:109], v[200:201], s[16:17], v[108:109] op_sel_hi:[1,0,1]
	v_pk_fma_f32 v[106:107], v[198:199], s[16:17], v[106:107] op_sel_hi:[1,0,1]
	global_store_dwordx4 v[150:151], v[106:109], off offset:512
	global_load_dwordx4 v[198:201], v[164:165], off offset:512
	s_waitcnt vmcnt(22)
	v_pk_fma_f32 v[104:105], v[206:207], s[16:17], v[104:105] op_sel_hi:[1,0,1]
	v_pk_fma_f32 v[102:103], v[204:205], s[16:17], v[102:103] op_sel_hi:[1,0,1]
	global_store_dwordx4 v[150:151], v[102:105], off offset:576
	global_load_dwordx4 v[204:207], v[164:165], off offset:576
	s_waitcnt vmcnt(23)
	v_pk_fma_f32 v[100:101], v[210:211], s[16:17], v[100:101] op_sel_hi:[1,0,1]
	v_pk_fma_f32 v[98:99], v[208:209], s[16:17], v[98:99] op_sel_hi:[1,0,1]
	global_store_dwordx4 v[154:155], v[98:101], off
	global_load_dwordx4 v[208:211], v[166:167], off
	s_waitcnt vmcnt(24)
	v_pk_fma_f32 v[96:97], v[214:215], s[16:17], v[96:97] op_sel_hi:[1,0,1]
	v_pk_fma_f32 v[94:95], v[212:213], s[16:17], v[94:95] op_sel_hi:[1,0,1]
	global_store_dwordx4 v[154:155], v[94:97], off offset:64
	global_load_dwordx4 v[212:215], v[166:167], off offset:64
	s_waitcnt vmcnt(25)
	v_pk_fma_f32 v[92:93], v[218:219], s[16:17], v[92:93] op_sel_hi:[1,0,1]
	v_pk_fma_f32 v[90:91], v[216:217], s[16:17], v[90:91] op_sel_hi:[1,0,1]
	global_store_dwordx4 v[154:155], v[90:93], off offset:512
	global_load_dwordx4 v[216:219], v[166:167], off offset:512
	s_waitcnt vmcnt(26)
	v_pk_fma_f32 v[88:89], v[222:223], s[16:17], v[88:89] op_sel_hi:[1,0,1]
	v_pk_fma_f32 v[86:87], v[220:221], s[16:17], v[86:87] op_sel_hi:[1,0,1]
	global_store_dwordx4 v[154:155], v[86:89], off offset:576
	global_load_dwordx4 v[220:223], v[166:167], off offset:576
	s_waitcnt vmcnt(27)
	v_pk_fma_f32 v[84:85], v[226:227], s[16:17], v[84:85] op_sel_hi:[1,0,1]
	v_pk_fma_f32 v[82:83], v[224:225], s[16:17], v[82:83] op_sel_hi:[1,0,1]
	global_store_dwordx4 v[156:157], v[82:85], off
	global_load_dwordx4 v[224:227], v[168:169], off
	s_waitcnt vmcnt(28)
	v_pk_fma_f32 v[80:81], v[230:231], s[16:17], v[80:81] op_sel_hi:[1,0,1]
	v_pk_fma_f32 v[78:79], v[228:229], s[16:17], v[78:79] op_sel_hi:[1,0,1]
	global_store_dwordx4 v[156:157], v[78:81], off offset:64
	global_load_dwordx4 v[228:231], v[168:169], off offset:64
	s_waitcnt vmcnt(29)
	v_pk_fma_f32 v[76:77], v[234:235], s[16:17], v[76:77] op_sel_hi:[1,0,1]
	v_pk_fma_f32 v[74:75], v[232:233], s[16:17], v[74:75] op_sel_hi:[1,0,1]
	global_store_dwordx4 v[156:157], v[74:77], off offset:512
	global_load_dwordx4 v[232:235], v[168:169], off offset:512
	s_waitcnt vmcnt(30)
	v_pk_fma_f32 v[72:73], v[238:239], s[16:17], v[72:73] op_sel_hi:[1,0,1]
	v_pk_fma_f32 v[70:71], v[236:237], s[16:17], v[70:71] op_sel_hi:[1,0,1]
	global_store_dwordx4 v[156:157], v[70:73], off offset:576
	global_load_dwordx4 v[236:239], v[168:169], off offset:576
	s_waitcnt vmcnt(30)
; DI bf16x4 pack4(float a, float b, float c, float d) { u32x2v u; u.x = pk2(a, b); u.y = pk2(c, d); return __builtin_bit_cast(bf16x4, u); }
; template <class Epi, class Sched>
; __device__ __forceinline__ void gemm_phase(PG8_LAS unsigned char* lds, const Gemm g, const Sched& S, const Epi& E) {
;     ...
;         if (!has_next) break;
;   DI void operator()(const f32x4 (&acc)[2][2][4][2], const pg8::Unit& u, int wr, int wc, int fr, int fq) const {
;     ...
;     for (int ai = 0; ai < 2; ++ai)
; #pragma unroll
;       for (int m = 0; m < 4; ++m) {
;         const int row = u.pm * 256 + 128 * ai + 64 * wr + 16 * m + fr;
; #pragma unroll
;         for (int bj = 0; bj < 2; ++bj)
; #pragma unroll
;           for (int n = 0; n < 2; ++n) {
;             const size_t idx = (size_t)row * 1024 + u.pn * 256 + 128 * bj + 32 * wc + 16 * n + 4 * fq;
;             const f32x4 a = acc[ai][bj][m][n];
;             if (MODE == 0) {
;               const unsigned g = *reinterpret_cast<const unsigned*>(reinterpret_cast<const unsigned char*>(p.ws + OFF_RB) + idx);
;               const float k = 1.f / 255.f;
;               st4(MERGED + idx, pack4((float)(g & 255u) * k * a[0], (float)((g >> 8) & 255u) * k * a[1], (float)((g >> 16) & 255u) * k * a[2], (float)(g >> 24) * k * a[3]));
;             } else {
;               f32x4 x = *reinterpret_cast<const f32x4*>(p.out + idx);
;               x = x * ALPHA + a;
;               *reinterpret_cast<f32x4*>(p.out + idx) = x;
;             }
	v_pk_fma_f32 v[68:69], v[172:173], s[16:17], v[68:69] op_sel_hi:[1,0,1]
	v_pk_fma_f32 v[66:67], v[170:171], s[16:17], v[66:67] op_sel_hi:[1,0,1]
	global_store_dwordx4 v[162:163], v[66:69], off
	s_waitcnt vmcnt(29)
	v_pk_fma_f32 v[64:65], v[176:177], s[16:17], v[64:65] op_sel_hi:[1,0,1]
	v_pk_fma_f32 v[62:63], v[174:175], s[16:17], v[62:63] op_sel_hi:[1,0,1]
	global_store_dwordx4 v[162:163], v[62:65], off offset:64
	s_waitcnt vmcnt(28)
	v_pk_fma_f32 v[60:61], v[180:181], s[16:17], v[60:61] op_sel_hi:[1,0,1]
	v_pk_fma_f32 v[58:59], v[178:179], s[16:17], v[58:59] op_sel_hi:[1,0,1]
	global_store_dwordx4 v[162:163], v[58:61], off offset:512
	s_waitcnt vmcnt(27)
	v_pk_fma_f32 v[56:57], v[188:189], s[16:17], v[56:57] op_sel_hi:[1,0,1]
	v_pk_fma_f32 v[54:55], v[186:187], s[16:17], v[54:55] op_sel_hi:[1,0,1]
	global_store_dwordx4 v[162:163], v[54:57], off offset:576
	s_waitcnt vmcnt(26)
	v_pk_fma_f32 v[52:53], v[192:193], s[16:17], v[52:53] op_sel_hi:[1,0,1]
	v_pk_fma_f32 v[50:51], v[190:191], s[16:17], v[50:51] op_sel_hi:[1,0,1]
	global_store_dwordx4 v[164:165], v[50:53], off
	s_waitcnt vmcnt(25)
	v_pk_fma_f32 v[48:49], v[196:197], s[16:17], v[48:49] op_sel_hi:[1,0,1]
	v_pk_fma_f32 v[46:47], v[194:195], s[16:17], v[46:47] op_sel_hi:[1,0,1]
	global_store_dwordx4 v[164:165], v[46:49], off offset:64
	s_waitcnt vmcnt(24)
	v_pk_fma_f32 v[44:45], v[200:201], s[16:17], v[44:45] op_sel_hi:[1,0,1]
	v_pk_fma_f32 v[42:43], v[198:199], s[16:17], v[42:43] op_sel_hi:[1,0,1]
	global_store_dwordx4 v[164:165], v[42:45], off offset:512
	s_waitcnt vmcnt(23)
	v_pk_fma_f32 v[40:41], v[206:207], s[16:17], v[40:41] op_sel_hi:[1,0,1]
	v_pk_fma_f32 v[38:39], v[204:205], s[16:17], v[38:39] op_sel_hi:[1,0,1]
	global_store_dwordx4 v[164:165], v[38:41], off offset:576
	s_waitcnt vmcnt(22)
	v_pk_fma_f32 v[36:37], v[210:211], s[16:17], v[36:37] op_sel_hi:[1,0,1]
	v_pk_fma_f32 v[34:35], v[208:209], s[16:17], v[34:35] op_sel_hi:[1,0,1]
	global_store_dwordx4 v[166:167], v[34:37], off
	s_waitcnt vmcnt(21)
	v_pk_fma_f32 v[32:33], v[214:215], s[16:17], v[32:33] op_sel_hi:[1,0,1]
	v_pk_fma_f32 v[30:31], v[212:213], s[16:17], v[30:31] op_sel_hi:[1,0,1]
	global_store_dwordx4 v[166:167], v[30:33], off offset:64
	s_waitcnt vmcnt(20)
	v_pk_fma_f32 v[28:29], v[218:219], s[16:17], v[28:29] op_sel_hi:[1,0,1]
	v_pk_fma_f32 v[26:27], v[216:217], s[16:17], v[26:27] op_sel_hi:[1,0,1]
	global_store_dwordx4 v[166:167], v[26:29], off offset:512
	s_waitcnt vmcnt(19)
	v_pk_fma_f32 v[24:25], v[222:223], s[16:17], v[24:25] op_sel_hi:[1,0,1]
	v_pk_fma_f32 v[22:23], v[220:221], s[16:17], v[22:23] op_sel_hi:[1,0,1]
	global_store_dwordx4 v[166:167], v[22:25], off offset:576
	s_waitcnt vmcnt(18)
	v_pk_fma_f32 v[14:15], v[226:227], s[16:17], v[14:15] op_sel_hi:[1,0,1]
	v_pk_fma_f32 v[12:13], v[224:225], s[16:17], v[12:13] op_sel_hi:[1,0,1]
	global_store_dwordx4 v[168:169], v[12:15], off
	s_waitcnt vmcnt(17)
	v_pk_fma_f32 v[10:11], v[230:231], s[16:17], v[10:11] op_sel_hi:[1,0,1]
	v_pk_fma_f32 v[8:9], v[228:229], s[16:17], v[8:9] op_sel_hi:[1,0,1]
	global_store_dwordx4 v[168:169], v[8:11], off offset:64
	s_waitcnt vmcnt(16)
	v_pk_fma_f32 v[6:7], v[234:235], s[16:17], v[6:7] op_sel_hi:[1,0,1]
	v_pk_fma_f32 v[4:5], v[232:233], s[16:17], v[4:5] op_sel_hi:[1,0,1]
	global_store_dwordx4 v[168:169], v[4:7], off offset:512
	s_waitcnt vmcnt(15)
	v_pk_fma_f32 v[2:3], v[238:239], s[16:17], v[2:3] op_sel_hi:[1,0,1]
	v_pk_fma_f32 v[0:1], v[236:237], s[16:17], v[0:1] op_sel_hi:[1,0,1]
	global_store_dwordx4 v[168:169], v[0:3], off offset:576
	s_mov_b32 s11, s2
	s_mov_b32 s10, s4
	s_mov_b64 s[14:15], s[8:9]
	s_mov_b64 s[12:13], s[6:7]
	s_and_b64 vcc, exec, s[0:1]
	s_cbranch_vccz .LBB0_2751
	s_waitcnt vmcnt(0)
	s_cmpk_gt_u32 s20, 0xff
	s_cbranch_scc1 .LBB0_2758
	s_barrier
